# K-loop memory segments reordered: all LDS fragment reads first, LDS-DMA address prep and issue behind them
# speedup vs baseline: 1.0017x; 1.0001x over previous
; #define PG8_STAGE(bufoff, gbase, voff) do { _Pragma("unroll") for (int _i = 0; _i < 2; ++_i) \
;         __builtin_amdgcn_global_load_lds((const unsigned*)((const char*)(gbase) + (voff)[_i]), (LAS unsigned*)(lds + (bufoff) + ldsw + _i * 8192), 16, 0, 0); } while (0)
; #define PG8_LDA(dst, b, h) do { _Pragma("unroll") for (int m = 0; m < 4; ++m) _Pragma("unroll") for (int k = 0; k < 2; ++k) dst[m][k] = *(const LAS bf16x8*)(lds + PG8_SA(b, h) + aoff + m * 2048 + k * 1024); } while (0)
; #define PG8_LDB(dst, b, h) do { _Pragma("unroll") for (int n = 0; n < 2; ++n) _Pragma("unroll") for (int k = 0; k < 2; ++k) dst[n][k] = *(const LAS bf16x8*)(lds + PG8_SB(b, h) + boff + n * 2048 + k * 1024); } while (0)
; #define PG8_MMA(ai, bj, At, Bt) do { __builtin_amdgcn_s_setprio(1); _Pragma("unroll") for (int m = 0; m < 4; ++m) _Pragma("unroll") for (int n = 0; n < 2; ++n) _Pragma("unroll") for (int k = 0; k < 2; ++k) \
;         acc[ai][bj][m][n] = __builtin_amdgcn_mfma_f32_16x16x32_bf16(Bt[n][k], At[m][k], acc[ai][bj][m][n], 0, 0, 0); __builtin_amdgcn_s_setprio(0); } while (0)
; #define PG8_WAIT_V(n) asm volatile("s_waitcnt vmcnt(" #n ")" ::: "memory")
; #define PG8_WAIT_L(n) asm volatile("s_waitcnt lgkmcnt(" #n ")" ::: "memory")
; #define PG8_BAR __builtin_amdgcn_s_barrier()
; template <class Epi, int AMODE>
; __device__ __forceinline__ void gemm_phase(LAS unsigned char* lds, const Gemm g, const StaticOrder& S, const Epi& E, int stagger_us, int tid_in) {
;     ...
;         const char* nA = has_next ? Abase + (size_t)nxt.pm * tstepA : cA; const char* nB = has_next ? (const char*)g.Bt + (size_t)nxt.pn * tstepB : cB;
;         for (int t = 0; t < nt; t += 2) {
;             const bool last = (t == nt - 2);
;             const char* a1 = cA + (size_t)(t + 1) * kstep;
;             const char* a2 = last ? nA : cA + (size_t)(t + 2) * kstep; const char* b2 = last ? nB : cB + (size_t)(t + 2) * kstep;
;             const char* a3 = a2 + kstep; const char* b3 = b2 + kstep;
;             PG8_LDB(B0, 0, 0); PG8_LDB(B1, 0, 1); PG8_SCHED; PG8_LDA(At, 0, 0); PG8_STAGE(PG8_SA(1, 1), a1 + hstepA, voffA);
;             PG8_WAIT_V(8); PG8_WAIT_L(0); PG8_BAR; PG8_MMA(0, 0, At, B0); PG8_MMA(0, 1, At, B1); PG8_BAR; PG8_SCHED;
;             PG8_LDA(At, 0, 1); PG8_STAGE(PG8_SB(0, 0), b2, voffB); PG8_STAGE(PG8_SB(0, 1), b2 + hstepB, voffB); PG8_STAGE(PG8_SA(0, 0), a2, voffA);
.LBB0_396:
	s_add_u32 s4, s60, 0xfff80080
	s_addc_u32 s5, s61, -1
	s_add_i32 s30, 0, 0x10000
	s_cmp_eq_u32 s29, 28
	s_cselect_b32 s7, s27, s5
	s_cselect_b32 s6, s28, s4
	v_add_u32_e32 v140, s30, v162
	s_cselect_b32 s5, s49, vcc_hi
	s_cselect_b32 s4, s51, vcc_lo
	s_add_i32 s44, 0, 0x14000
	ds_read_b128 v[144:147], v140
	ds_read_b128 v[148:151], v140 offset:1024
	ds_read_b128 v[152:155], v140 offset:2048
	ds_read_b128 v[156:159], v140 offset:3072
	v_add_u32_e32 v140, s44, v162
	ds_read_b128 v[166:169], v140
	ds_read_b128 v[170:173], v140 offset:1024
	ds_read_b128 v[174:177], v140 offset:2048
	ds_read_b128 v[178:181], v140 offset:3072
	v_lshl_add_u64 v[140:141], s[60:61], 0, v[136:137]
	s_add_i32 m0, s57, 0xc000
	ds_read_b128 v[182:185], v164
	ds_read_b128 v[186:189], v164 offset:1024
	ds_read_b128 v[190:193], v164 offset:2048
	ds_read_b128 v[194:197], v164 offset:3072
	ds_read_b128 v[198:201], v164 offset:4096
	ds_read_b128 v[202:205], v164 offset:5120
	ds_read_b128 v[206:209], v164 offset:6144
	ds_read_b128 v[210:213], v164 offset:7168
	global_load_lds_dwordx4 v[140:141], off
	s_add_i32 m0, s57, 0xe000
	v_lshl_add_u64 v[140:141], s[60:61], 0, v[138:139]
	global_load_lds_dwordx4 v[140:141], off
	s_setprio 1
	s_waitcnt vmcnt(8) lgkmcnt(0)
	s_barrier
	v_mfma_f32_16x16x32_bf16 v[126:129], v[144:147], v[182:185], v[126:129]
	v_mfma_f32_16x16x32_bf16 v[122:125], v[152:155], v[182:185], v[122:125]
	v_mfma_f32_16x16x32_bf16 v[110:113], v[144:147], v[190:193], v[110:113]
	v_mfma_f32_16x16x32_bf16 v[106:109], v[152:155], v[190:193], v[106:109]
	v_mfma_f32_16x16x32_bf16 v[94:97], v[144:147], v[198:201], v[94:97]
	v_mfma_f32_16x16x32_bf16 v[90:93], v[152:155], v[198:201], v[90:93]
	v_mfma_f32_16x16x32_bf16 v[78:81], v[144:147], v[206:209], v[78:81]
	v_mfma_f32_16x16x32_bf16 v[74:77], v[152:155], v[206:209], v[74:77]
	v_mfma_f32_16x16x32_bf16 v[126:129], v[148:151], v[186:189], v[126:129]
	v_mfma_f32_16x16x32_bf16 v[122:125], v[156:159], v[186:189], v[122:125]
	v_mfma_f32_16x16x32_bf16 v[110:113], v[148:151], v[194:197], v[110:113]
	v_mfma_f32_16x16x32_bf16 v[106:109], v[156:159], v[194:197], v[106:109]
	v_mfma_f32_16x16x32_bf16 v[94:97], v[148:151], v[202:205], v[94:97]
	v_mfma_f32_16x16x32_bf16 v[90:93], v[156:159], v[202:205], v[90:93]
	v_mfma_f32_16x16x32_bf16 v[78:81], v[148:151], v[210:213], v[78:81]
	v_mfma_f32_16x16x32_bf16 v[74:77], v[156:159], v[210:213], v[74:77]
	v_mfma_f32_16x16x32_bf16 v[118:121], v[166:169], v[182:185], v[118:121]
	v_mfma_f32_16x16x32_bf16 v[114:117], v[174:177], v[182:185], v[114:117]
	v_mfma_f32_16x16x32_bf16 v[102:105], v[166:169], v[190:193], v[102:105]
	v_mfma_f32_16x16x32_bf16 v[98:101], v[174:177], v[190:193], v[98:101]
	v_mfma_f32_16x16x32_bf16 v[86:89], v[166:169], v[198:201], v[86:89]
	v_mfma_f32_16x16x32_bf16 v[82:85], v[174:177], v[198:201], v[82:85]
	v_mfma_f32_16x16x32_bf16 v[70:73], v[166:169], v[206:209], v[70:73]
	v_mfma_f32_16x16x32_bf16 v[66:69], v[174:177], v[206:209], v[66:69]
	v_mfma_f32_16x16x32_bf16 v[118:121], v[170:173], v[186:189], v[118:121]
	v_mfma_f32_16x16x32_bf16 v[114:117], v[178:181], v[186:189], v[114:117]
	v_mfma_f32_16x16x32_bf16 v[102:105], v[170:173], v[194:197], v[102:105]
	v_mfma_f32_16x16x32_bf16 v[98:101], v[178:181], v[194:197], v[98:101]
	v_mfma_f32_16x16x32_bf16 v[86:89], v[170:173], v[202:205], v[86:89]
	v_mfma_f32_16x16x32_bf16 v[82:85], v[178:181], v[202:205], v[82:85]
	v_mfma_f32_16x16x32_bf16 v[70:73], v[170:173], v[210:213], v[70:73]
	v_mfma_f32_16x16x32_bf16 v[66:69], v[178:181], v[210:213], v[66:69]
	s_setprio 0
	s_barrier
	ds_read_b128 v[182:185], v164 offset:16384
	ds_read_b128 v[186:189], v164 offset:17408
	ds_read_b128 v[190:193], v164 offset:18432
	ds_read_b128 v[194:197], v164 offset:19456
	ds_read_b128 v[198:201], v164 offset:20480
	ds_read_b128 v[202:205], v164 offset:21504
	ds_read_b128 v[206:209], v164 offset:22528
	ds_read_b128 v[210:213], v164 offset:23552
	s_add_i32 s30, s30, s66
	s_mov_b32 m0, s30
	v_lshl_add_u64 v[140:141], s[4:5], 0, v[0:1]
	global_load_lds_dwordx4 v[140:141], off
	s_add_i32 m0, s30, 0x2000
	s_add_u32 s30, s4, 0x80000
	v_lshl_add_u64 v[160:161], s[4:5], 0, v[130:131]
	s_addc_u32 s31, s5, 0
	s_add_i32 s44, s44, s66
	global_load_lds_dwordx4 v[160:161], off
	v_lshl_add_u64 v[214:215], s[30:31], 0, v[0:1]
	s_mov_b32 m0, s44
	v_lshl_add_u64 v[216:217], s[6:7], 0, v[132:133]
	global_load_lds_dwordx4 v[214:215], off
	s_add_i32 m0, s44, 0x2000
	v_lshl_add_u64 v[214:215], s[30:31], 0, v[130:131]
	global_load_lds_dwordx4 v[214:215], off
	s_mov_b32 m0, s57
	v_lshl_add_u64 v[214:215], s[6:7], 0, v[134:135]
	global_load_lds_dwordx4 v[214:215], off
	s_mov_b32 m0, s59
	s_nop 0
	global_load_lds_dwordx4 v[216:217], off
	s_setprio 1
	s_waitcnt vmcnt(8) lgkmcnt(0)
	s_barrier
; #define PG8_STAGE(bufoff, gbase, voff) do { _Pragma("unroll") for (int _i = 0; _i < 2; ++_i) \
;         __builtin_amdgcn_global_load_lds((const unsigned*)((const char*)(gbase) + (voff)[_i]), (LAS unsigned*)(lds + (bufoff) + ldsw + _i * 8192), 16, 0, 0); } while (0)
; #define PG8_LDA(dst, b, h) do { _Pragma("unroll") for (int m = 0; m < 4; ++m) _Pragma("unroll") for (int k = 0; k < 2; ++k) dst[m][k] = *(const LAS bf16x8*)(lds + PG8_SA(b, h) + aoff + m * 2048 + k * 1024); } while (0)
; #define PG8_LDB(dst, b, h) do { _Pragma("unroll") for (int n = 0; n < 2; ++n) _Pragma("unroll") for (int k = 0; k < 2; ++k) dst[n][k] = *(const LAS bf16x8*)(lds + PG8_SB(b, h) + boff + n * 2048 + k * 1024); } while (0)
; #define PG8_MMA(ai, bj, At, Bt) do { __builtin_amdgcn_s_setprio(1); _Pragma("unroll") for (int m = 0; m < 4; ++m) _Pragma("unroll") for (int n = 0; n < 2; ++n) _Pragma("unroll") for (int k = 0; k < 2; ++k) \
;         acc[ai][bj][m][n] = __builtin_amdgcn_mfma_f32_16x16x32_bf16(Bt[n][k], At[m][k], acc[ai][bj][m][n], 0, 0, 0); __builtin_amdgcn_s_setprio(0); } while (0)
; #define PG8_WAIT_V(n) asm volatile("s_waitcnt vmcnt(" #n ")" ::: "memory")
; #define PG8_WAIT_L(n) asm volatile("s_waitcnt lgkmcnt(" #n ")" ::: "memory")
; #define PG8_BAR __builtin_amdgcn_s_barrier()
; #define PG8_SCHED __builtin_amdgcn_sched_barrier(0)
; template <class Epi, int AMODE>
; __device__ __forceinline__ void gemm_phase(LAS unsigned char* lds, const Gemm g, const StaticOrder& S, const Epi& E, int stagger_us, int tid_in) {
;     ...
;             PG8_WAIT_V(8); PG8_WAIT_L(0); PG8_BAR; PG8_MMA(1, 0, At, B0); PG8_MMA(1, 1, At, B1); PG8_BAR; PG8_SCHED;
;             PG8_LDB(B0, 1, 0); PG8_LDB(B1, 1, 1); PG8_SCHED; PG8_LDA(At, 1, 0); PG8_STAGE(PG8_SA(0, 1), a2 + hstepA, voffA);
;             PG8_WAIT_V(8); PG8_WAIT_L(0); PG8_BAR; PG8_MMA(0, 0, At, B0); PG8_MMA(0, 1, At, B1); PG8_BAR; PG8_SCHED;
	v_mfma_f32_16x16x32_bf16 v[62:65], v[144:147], v[182:185], v[62:65]
	v_mfma_f32_16x16x32_bf16 v[58:61], v[152:155], v[182:185], v[58:61]
	v_mfma_f32_16x16x32_bf16 v[46:49], v[144:147], v[190:193], v[46:49]
	v_mfma_f32_16x16x32_bf16 v[42:45], v[152:155], v[190:193], v[42:45]
	v_mfma_f32_16x16x32_bf16 v[30:33], v[144:147], v[198:201], v[30:33]
	v_mfma_f32_16x16x32_bf16 v[26:29], v[152:155], v[198:201], v[26:29]
	v_mfma_f32_16x16x32_bf16 v[14:17], v[144:147], v[206:209], v[14:17]
	v_mfma_f32_16x16x32_bf16 v[10:13], v[152:155], v[206:209], v[10:13]
	v_mfma_f32_16x16x32_bf16 v[62:65], v[148:151], v[186:189], v[62:65]
	v_mfma_f32_16x16x32_bf16 v[58:61], v[156:159], v[186:189], v[58:61]
	v_mfma_f32_16x16x32_bf16 v[46:49], v[148:151], v[194:197], v[46:49]
	v_mfma_f32_16x16x32_bf16 v[42:45], v[156:159], v[194:197], v[42:45]
	v_mfma_f32_16x16x32_bf16 v[30:33], v[148:151], v[202:205], v[30:33]
	v_mfma_f32_16x16x32_bf16 v[26:29], v[156:159], v[202:205], v[26:29]
	v_mfma_f32_16x16x32_bf16 v[14:17], v[148:151], v[210:213], v[14:17]
	v_mfma_f32_16x16x32_bf16 v[10:13], v[156:159], v[210:213], v[10:13]
	v_mfma_f32_16x16x32_bf16 v[54:57], v[166:169], v[182:185], v[54:57]
	v_mfma_f32_16x16x32_bf16 v[50:53], v[174:177], v[182:185], v[50:53]
	v_mfma_f32_16x16x32_bf16 v[38:41], v[166:169], v[190:193], v[38:41]
	v_mfma_f32_16x16x32_bf16 v[34:37], v[174:177], v[190:193], v[34:37]
	v_mfma_f32_16x16x32_bf16 v[22:25], v[166:169], v[198:201], v[22:25]
	v_mfma_f32_16x16x32_bf16 v[18:21], v[174:177], v[198:201], v[18:21]
	v_mfma_f32_16x16x32_bf16 v[6:9], v[166:169], v[206:209], v[6:9]
	v_mfma_f32_16x16x32_bf16 v[2:5], v[174:177], v[206:209], v[2:5]
	v_mfma_f32_16x16x32_bf16 v[54:57], v[170:173], v[186:189], v[54:57]
	v_mfma_f32_16x16x32_bf16 v[50:53], v[178:181], v[186:189], v[50:53]
	v_mfma_f32_16x16x32_bf16 v[38:41], v[170:173], v[194:197], v[38:41]
	v_mfma_f32_16x16x32_bf16 v[34:37], v[178:181], v[194:197], v[34:37]
	v_mfma_f32_16x16x32_bf16 v[22:25], v[170:173], v[202:205], v[22:25]
	v_mfma_f32_16x16x32_bf16 v[18:21], v[178:181], v[202:205], v[18:21]
	v_mfma_f32_16x16x32_bf16 v[6:9], v[170:173], v[210:213], v[6:9]
	v_mfma_f32_16x16x32_bf16 v[2:5], v[178:181], v[210:213], v[2:5]
	s_setprio 0
	s_barrier
	s_add_i32 s30, 0, 0x18000
	v_add_u32_e32 v142, s30, v162
	s_add_i32 s31, 0, 0x1c000
	ds_read_b128 v[144:147], v142
	ds_read_b128 v[148:151], v142 offset:1024
	ds_read_b128 v[152:155], v142 offset:2048
	ds_read_b128 v[156:159], v142 offset:3072
	v_add_u32_e32 v142, s31, v162
	ds_read_b128 v[166:169], v142
	ds_read_b128 v[170:173], v142 offset:1024
	ds_read_b128 v[174:177], v142 offset:2048
	ds_read_b128 v[178:181], v142 offset:3072
	s_add_u32 s6, s6, 0x80000
	s_addc_u32 s7, s7, 0
	s_mov_b32 m0, s87
	v_lshl_add_u64 v[218:219], s[6:7], 0, v[134:135]
	ds_read_b128 v[182:185], v164 offset:32768
	ds_read_b128 v[186:189], v164 offset:33792
	ds_read_b128 v[190:193], v164 offset:34816
	ds_read_b128 v[194:197], v164 offset:35840
	ds_read_b128 v[198:201], v164 offset:36864
	ds_read_b128 v[202:205], v164 offset:37888
	ds_read_b128 v[206:209], v164 offset:38912
	ds_read_b128 v[210:213], v164 offset:39936
	global_load_lds_dwordx4 v[218:219], off
	s_mov_b32 m0, s91
	v_lshl_add_u64 v[218:219], s[6:7], 0, v[132:133]
	global_load_lds_dwordx4 v[218:219], off
	s_setprio 1
	s_waitcnt vmcnt(8) lgkmcnt(0)
	s_barrier
	v_mfma_f32_16x16x32_bf16 v[126:129], v[144:147], v[182:185], v[126:129]
	v_mfma_f32_16x16x32_bf16 v[122:125], v[152:155], v[182:185], v[122:125]
	v_mfma_f32_16x16x32_bf16 v[110:113], v[144:147], v[190:193], v[110:113]
	v_mfma_f32_16x16x32_bf16 v[106:109], v[152:155], v[190:193], v[106:109]
	v_mfma_f32_16x16x32_bf16 v[94:97], v[144:147], v[198:201], v[94:97]
	v_mfma_f32_16x16x32_bf16 v[90:93], v[152:155], v[198:201], v[90:93]
	v_mfma_f32_16x16x32_bf16 v[78:81], v[144:147], v[206:209], v[78:81]
	v_mfma_f32_16x16x32_bf16 v[74:77], v[152:155], v[206:209], v[74:77]
	v_mfma_f32_16x16x32_bf16 v[126:129], v[148:151], v[186:189], v[126:129]
	v_mfma_f32_16x16x32_bf16 v[122:125], v[156:159], v[186:189], v[122:125]
	v_mfma_f32_16x16x32_bf16 v[110:113], v[148:151], v[194:197], v[110:113]
	v_mfma_f32_16x16x32_bf16 v[106:109], v[156:159], v[194:197], v[106:109]
	v_mfma_f32_16x16x32_bf16 v[94:97], v[148:151], v[202:205], v[94:97]
	v_mfma_f32_16x16x32_bf16 v[90:93], v[156:159], v[202:205], v[90:93]
	v_mfma_f32_16x16x32_bf16 v[78:81], v[148:151], v[210:213], v[78:81]
	v_mfma_f32_16x16x32_bf16 v[74:77], v[156:159], v[210:213], v[74:77]
	v_mfma_f32_16x16x32_bf16 v[118:121], v[166:169], v[182:185], v[118:121]
	v_mfma_f32_16x16x32_bf16 v[114:117], v[174:177], v[182:185], v[114:117]
	v_mfma_f32_16x16x32_bf16 v[102:105], v[166:169], v[190:193], v[102:105]
	v_mfma_f32_16x16x32_bf16 v[98:101], v[174:177], v[190:193], v[98:101]
	v_mfma_f32_16x16x32_bf16 v[86:89], v[166:169], v[198:201], v[86:89]
	v_mfma_f32_16x16x32_bf16 v[82:85], v[174:177], v[198:201], v[82:85]
	v_mfma_f32_16x16x32_bf16 v[70:73], v[166:169], v[206:209], v[70:73]
	v_mfma_f32_16x16x32_bf16 v[66:69], v[174:177], v[206:209], v[66:69]
	v_mfma_f32_16x16x32_bf16 v[118:121], v[170:173], v[186:189], v[118:121]
	v_mfma_f32_16x16x32_bf16 v[114:117], v[178:181], v[186:189], v[114:117]
	v_mfma_f32_16x16x32_bf16 v[102:105], v[170:173], v[194:197], v[102:105]
	v_mfma_f32_16x16x32_bf16 v[98:101], v[178:181], v[194:197], v[98:101]
	v_mfma_f32_16x16x32_bf16 v[86:89], v[170:173], v[202:205], v[86:89]
	v_mfma_f32_16x16x32_bf16 v[82:85], v[178:181], v[202:205], v[82:85]
	v_mfma_f32_16x16x32_bf16 v[70:73], v[170:173], v[210:213], v[70:73]
	v_mfma_f32_16x16x32_bf16 v[66:69], v[178:181], v[210:213], v[66:69]
	s_setprio 0
	s_barrier
; #define PG8_STAGE(bufoff, gbase, voff) do { _Pragma("unroll") for (int _i = 0; _i < 2; ++_i) \
;         __builtin_amdgcn_global_load_lds((const unsigned*)((const char*)(gbase) + (voff)[_i]), (LAS unsigned*)(lds + (bufoff) + ldsw + _i * 8192), 16, 0, 0); } while (0)
; #define PG8_LDA(dst, b, h) do { _Pragma("unroll") for (int m = 0; m < 4; ++m) _Pragma("unroll") for (int k = 0; k < 2; ++k) dst[m][k] = *(const LAS bf16x8*)(lds + PG8_SA(b, h) + aoff + m * 2048 + k * 1024); } while (0)
; #define PG8_MMA(ai, bj, At, Bt) do { __builtin_amdgcn_s_setprio(1); _Pragma("unroll") for (int m = 0; m < 4; ++m) _Pragma("unroll") for (int n = 0; n < 2; ++n) _Pragma("unroll") for (int k = 0; k < 2; ++k) \
;         acc[ai][bj][m][n] = __builtin_amdgcn_mfma_f32_16x16x32_bf16(Bt[n][k], At[m][k], acc[ai][bj][m][n], 0, 0, 0); __builtin_amdgcn_s_setprio(0); } while (0)
; #define PG8_WAIT_V(n) asm volatile("s_waitcnt vmcnt(" #n ")" ::: "memory")
; #define PG8_WAIT_L(n) asm volatile("s_waitcnt lgkmcnt(" #n ")" ::: "memory")
; #define PG8_BAR __builtin_amdgcn_s_barrier()
; #define PG8_SCHED __builtin_amdgcn_sched_barrier(0)
; template <class Epi, int AMODE>
; __device__ __forceinline__ void gemm_phase(LAS unsigned char* lds, const Gemm g, const StaticOrder& S, const Epi& E, int stagger_us, int tid_in) {
;     ...
;             PG8_LDA(At, 1, 1); PG8_STAGE(PG8_SB(1, 0), b3, voffB); PG8_STAGE(PG8_SB(1, 1), b3 + hstepB, voffB); PG8_STAGE(PG8_SA(1, 0), a3, voffA);
;             PG8_WAIT_V(8); PG8_WAIT_L(0); PG8_BAR; PG8_MMA(1, 0, At, B0); PG8_MMA(1, 1, At, B1); PG8_BAR; PG8_SCHED;
	ds_read_b128 v[182:185], v164 offset:49152
	ds_read_b128 v[186:189], v164 offset:50176
	ds_read_b128 v[190:193], v164 offset:51200
	ds_read_b128 v[194:197], v164 offset:52224
	ds_read_b128 v[198:201], v164 offset:53248
	ds_read_b128 v[202:205], v164 offset:54272
	ds_read_b128 v[206:209], v164 offset:55296
	ds_read_b128 v[210:213], v164 offset:56320
	s_add_i32 s6, s30, s66
	s_mov_b32 m0, s6
	v_lshl_add_u64 v[140:141], v[140:141], 0, s[74:75]
	global_load_lds_dwordx4 v[140:141], off
	s_add_i32 m0, s6, 0x2000
	s_add_u32 s4, s4, 0x80080
	v_lshl_add_u64 v[140:141], v[160:161], 0, s[74:75]
	s_addc_u32 s5, s5, 0
	s_add_i32 s6, s31, s66
	global_load_lds_dwordx4 v[140:141], off
	s_mov_b32 m0, s6
	v_lshl_add_u64 v[140:141], s[4:5], 0, v[0:1]
	global_load_lds_dwordx4 v[140:141], off
	s_add_i32 m0, s6, 0x2000
	v_lshl_add_u64 v[140:141], s[4:5], 0, v[130:131]
	global_load_lds_dwordx4 v[140:141], off
	s_mov_b32 m0, s95
	v_lshl_add_u64 v[140:141], v[214:215], 0, s[74:75]
	global_load_lds_dwordx4 v[140:141], off
	s_mov_b32 m0, s96
	v_lshl_add_u64 v[140:141], v[216:217], 0, s[74:75]
	global_load_lds_dwordx4 v[140:141], off
	s_setprio 1
	s_waitcnt vmcnt(8) lgkmcnt(0)
	s_barrier
	v_mfma_f32_16x16x32_bf16 v[62:65], v[144:147], v[182:185], v[62:65]
	v_mfma_f32_16x16x32_bf16 v[58:61], v[152:155], v[182:185], v[58:61]
	v_mfma_f32_16x16x32_bf16 v[46:49], v[144:147], v[190:193], v[46:49]
	v_mfma_f32_16x16x32_bf16 v[42:45], v[152:155], v[190:193], v[42:45]
	v_mfma_f32_16x16x32_bf16 v[30:33], v[144:147], v[198:201], v[30:33]
	v_mfma_f32_16x16x32_bf16 v[26:29], v[152:155], v[198:201], v[26:29]
	v_mfma_f32_16x16x32_bf16 v[14:17], v[144:147], v[206:209], v[14:17]
	v_mfma_f32_16x16x32_bf16 v[10:13], v[152:155], v[206:209], v[10:13]
	v_mfma_f32_16x16x32_bf16 v[62:65], v[148:151], v[186:189], v[62:65]
	v_mfma_f32_16x16x32_bf16 v[58:61], v[156:159], v[186:189], v[58:61]
	v_mfma_f32_16x16x32_bf16 v[46:49], v[148:151], v[194:197], v[46:49]
	v_mfma_f32_16x16x32_bf16 v[42:45], v[156:159], v[194:197], v[42:45]
	v_mfma_f32_16x16x32_bf16 v[30:33], v[148:151], v[202:205], v[30:33]
	v_mfma_f32_16x16x32_bf16 v[26:29], v[156:159], v[202:205], v[26:29]
	v_mfma_f32_16x16x32_bf16 v[14:17], v[148:151], v[210:213], v[14:17]
	v_mfma_f32_16x16x32_bf16 v[10:13], v[156:159], v[210:213], v[10:13]
	v_mfma_f32_16x16x32_bf16 v[54:57], v[166:169], v[182:185], v[54:57]
	v_mfma_f32_16x16x32_bf16 v[50:53], v[174:177], v[182:185], v[50:53]
	v_mfma_f32_16x16x32_bf16 v[38:41], v[166:169], v[190:193], v[38:41]
	v_mfma_f32_16x16x32_bf16 v[34:37], v[174:177], v[190:193], v[34:37]
	v_mfma_f32_16x16x32_bf16 v[22:25], v[166:169], v[198:201], v[22:25]
	v_mfma_f32_16x16x32_bf16 v[18:21], v[174:177], v[198:201], v[18:21]
	v_mfma_f32_16x16x32_bf16 v[6:9], v[166:169], v[206:209], v[6:9]
	v_mfma_f32_16x16x32_bf16 v[2:5], v[174:177], v[206:209], v[2:5]
	v_mfma_f32_16x16x32_bf16 v[54:57], v[170:173], v[186:189], v[54:57]
	v_mfma_f32_16x16x32_bf16 v[50:53], v[178:181], v[186:189], v[50:53]
	v_mfma_f32_16x16x32_bf16 v[38:41], v[170:173], v[194:197], v[38:41]
	v_mfma_f32_16x16x32_bf16 v[34:37], v[178:181], v[194:197], v[34:37]
	v_mfma_f32_16x16x32_bf16 v[22:25], v[170:173], v[202:205], v[22:25]
	v_mfma_f32_16x16x32_bf16 v[18:21], v[178:181], v[202:205], v[18:21]
	v_mfma_f32_16x16x32_bf16 v[6:9], v[170:173], v[210:213], v[6:9]
	v_mfma_f32_16x16x32_bf16 v[2:5], v[178:181], v[210:213], v[2:5]
	s_setprio 0
	s_barrier
	s_add_i32 s29, s29, 2
	s_add_u32 s60, s60, 0x100
	s_addc_u32 s61, s61, 0
	s_add_u32 vcc_lo, vcc_lo, 0x100
	s_addc_u32 vcc_hi, vcc_hi, 0
	s_cmp_gt_u32 s29, 29
	s_cbranch_scc0 .LBB0_396
	s_and_b64 vcc, exec, s[46:47]
	s_cbranch_vccz .LBB0_399
	s_barrier

; #define PG8_STAGE(bufoff, gbase, voff) do { _Pragma("unroll") for (int _i = 0; _i < 2; ++_i) \
;         __builtin_amdgcn_global_load_lds((const unsigned*)((const char*)(gbase) + (voff)[_i]), (LAS unsigned*)(lds + (bufoff) + ldsw + _i * 8192), 16, 0, 0); } while (0)
; #define PG8_LDA(dst, b, h) do { _Pragma("unroll") for (int m = 0; m < 4; ++m) _Pragma("unroll") for (int k = 0; k < 2; ++k) dst[m][k] = *(const LAS bf16x8*)(lds + PG8_SA(b, h) + aoff + m * 2048 + k * 1024); } while (0)
; #define PG8_LDB(dst, b, h) do { _Pragma("unroll") for (int n = 0; n < 2; ++n) _Pragma("unroll") for (int k = 0; k < 2; ++k) dst[n][k] = *(const LAS bf16x8*)(lds + PG8_SB(b, h) + boff + n * 2048 + k * 1024); } while (0)
; #define PG8_MMA(ai, bj, At, Bt) do { __builtin_amdgcn_s_setprio(1); _Pragma("unroll") for (int m = 0; m < 4; ++m) _Pragma("unroll") for (int n = 0; n < 2; ++n) _Pragma("unroll") for (int k = 0; k < 2; ++k) \
;         acc[ai][bj][m][n] = __builtin_amdgcn_mfma_f32_16x16x32_bf16(Bt[n][k], At[m][k], acc[ai][bj][m][n], 0, 0, 0); __builtin_amdgcn_s_setprio(0); } while (0)
; #define PG8_WAIT_V(n) asm volatile("s_waitcnt vmcnt(" #n ")" ::: "memory")
; #define PG8_WAIT_L(n) asm volatile("s_waitcnt lgkmcnt(" #n ")" ::: "memory")
; #define PG8_BAR __builtin_amdgcn_s_barrier()
; template <class Epi, int AMODE>
; __device__ __forceinline__ void gemm_phase(LAS unsigned char* lds, const Gemm g, const StaticOrder& S, const Epi& E, int stagger_us, int tid_in) {
;     ...
;         const char* nA = has_next ? Abase + (size_t)nxt.pm * tstepA : cA; const char* nB = has_next ? (const char*)g.Bt + (size_t)nxt.pn * tstepB : cB;
;         for (int t = 0; t < nt; t += 2) {
;             const bool last = (t == nt - 2);
;             const char* a1 = cA + (size_t)(t + 1) * kstep;
;             const char* a2 = last ? nA : cA + (size_t)(t + 2) * kstep; const char* b2 = last ? nB : cB + (size_t)(t + 2) * kstep;
;             const char* a3 = a2 + kstep; const char* b3 = b2 + kstep;
;             PG8_LDB(B0, 0, 0); PG8_LDB(B1, 0, 1); PG8_SCHED; PG8_LDA(At, 0, 0); PG8_STAGE(PG8_SA(1, 1), a1 + hstepA, voffA);
;             PG8_WAIT_V(8); PG8_WAIT_L(0); PG8_BAR; PG8_MMA(0, 0, At, B0); PG8_MMA(0, 1, At, B1); PG8_BAR; PG8_SCHED;
;             PG8_LDA(At, 0, 1); PG8_STAGE(PG8_SB(0, 0), b2, voffB); PG8_STAGE(PG8_SB(0, 1), b2 + hstepB, voffB); PG8_STAGE(PG8_SA(0, 0), a2, voffA);
.LBB0_1199:
	s_add_i32 s34, 0, 0x10000
	s_add_i32 s35, 0, 0x14000
	v_add_u32_e32 v62, s34, v205
	v_add_u32_e32 v158, s35, v205
	ds_read_b128 v[50:53], v62
	ds_read_b128 v[54:57], v62 offset:1024
	ds_read_b128 v[58:61], v62 offset:2048
	ds_read_b128 v[62:65], v62 offset:3072
	ds_read_b128 v[146:149], v158
	ds_read_b128 v[150:153], v158 offset:1024
	ds_read_b128 v[154:157], v158 offset:2048
	ds_read_b128 v[158:161], v158 offset:3072
	ds_read_b128 v[162:165], v207
	ds_read_b128 v[166:169], v207 offset:1024
	ds_read_b128 v[170:173], v207 offset:2048
	ds_read_b128 v[180:183], v207 offset:3072
	ds_read_b128 v[184:187], v207 offset:4096
	ds_read_b128 v[188:191], v207 offset:5120
	ds_read_b128 v[192:195], v207 offset:6144
	ds_read_b128 v[196:199], v207 offset:7168
	s_add_u32 s4, s46, 0x100
	s_addc_u32 s5, s47, 0
	s_cmp_eq_u32 s31, 28
	s_cselect_b32 s95, s61, s5
	s_cselect_b32 s94, vcc_lo, s4
	s_cselect_b32 s7, s59, s30
	s_cselect_b32 s6, vcc_hi, s29
	s_add_i32 m0, s66, 0xc000
	v_lshl_add_u64 v[200:201], s[46:47], 0, v[176:177]
	global_load_lds_dwordx4 v[200:201], off
	s_add_i32 m0, s66, 0xe000
	v_lshl_add_u64 v[200:201], s[46:47], 0, v[178:179]
	global_load_lds_dwordx4 v[200:201], off
	s_setprio 1
	s_waitcnt vmcnt(8) lgkmcnt(0)
	s_barrier
	v_mfma_f32_16x16x32_bf16 v[142:145], v[50:53], v[162:165], v[142:145]
	v_mfma_f32_16x16x32_bf16 v[138:141], v[58:61], v[162:165], v[138:141]
	v_mfma_f32_16x16x32_bf16 v[126:129], v[50:53], v[170:173], v[126:129]
	v_mfma_f32_16x16x32_bf16 v[122:125], v[58:61], v[170:173], v[122:125]
	v_mfma_f32_16x16x32_bf16 v[110:113], v[50:53], v[184:187], v[110:113]
	v_mfma_f32_16x16x32_bf16 v[106:109], v[58:61], v[184:187], v[106:109]
	v_mfma_f32_16x16x32_bf16 v[94:97], v[50:53], v[192:195], v[94:97]
	v_mfma_f32_16x16x32_bf16 v[90:93], v[58:61], v[192:195], v[90:93]
	v_mfma_f32_16x16x32_bf16 v[142:145], v[54:57], v[166:169], v[142:145]
	v_mfma_f32_16x16x32_bf16 v[138:141], v[62:65], v[166:169], v[138:141]
	v_mfma_f32_16x16x32_bf16 v[126:129], v[54:57], v[180:183], v[126:129]
	v_mfma_f32_16x16x32_bf16 v[122:125], v[62:65], v[180:183], v[122:125]
	v_mfma_f32_16x16x32_bf16 v[110:113], v[54:57], v[188:191], v[110:113]
	v_mfma_f32_16x16x32_bf16 v[106:109], v[62:65], v[188:191], v[106:109]
	v_mfma_f32_16x16x32_bf16 v[94:97], v[54:57], v[196:199], v[94:97]
	v_mfma_f32_16x16x32_bf16 v[90:93], v[62:65], v[196:199], v[90:93]
	v_mfma_f32_16x16x32_bf16 v[134:137], v[146:149], v[162:165], v[134:137]
	v_mfma_f32_16x16x32_bf16 v[130:133], v[154:157], v[162:165], v[130:133]
	v_mfma_f32_16x16x32_bf16 v[118:121], v[146:149], v[170:173], v[118:121]
	v_mfma_f32_16x16x32_bf16 v[114:117], v[154:157], v[170:173], v[114:117]
	v_mfma_f32_16x16x32_bf16 v[102:105], v[146:149], v[184:187], v[102:105]
	v_mfma_f32_16x16x32_bf16 v[98:101], v[154:157], v[184:187], v[98:101]
	v_mfma_f32_16x16x32_bf16 v[86:89], v[146:149], v[192:195], v[86:89]
	v_mfma_f32_16x16x32_bf16 v[82:85], v[154:157], v[192:195], v[82:85]
	v_mfma_f32_16x16x32_bf16 v[134:137], v[150:153], v[166:169], v[134:137]
	v_mfma_f32_16x16x32_bf16 v[130:133], v[158:161], v[166:169], v[130:133]
	v_mfma_f32_16x16x32_bf16 v[118:121], v[150:153], v[180:183], v[118:121]
	v_mfma_f32_16x16x32_bf16 v[114:117], v[158:161], v[180:183], v[114:117]
	v_mfma_f32_16x16x32_bf16 v[102:105], v[150:153], v[188:191], v[102:105]
	v_mfma_f32_16x16x32_bf16 v[98:101], v[158:161], v[188:191], v[98:101]
	v_mfma_f32_16x16x32_bf16 v[86:89], v[150:153], v[196:199], v[86:89]
	v_mfma_f32_16x16x32_bf16 v[82:85], v[158:161], v[196:199], v[82:85]
	s_setprio 0
	s_barrier
	ds_read_b128 v[162:165], v207 offset:16384
	ds_read_b128 v[166:169], v207 offset:17408
	ds_read_b128 v[170:173], v207 offset:18432
	ds_read_b128 v[180:183], v207 offset:19456
	ds_read_b128 v[184:187], v207 offset:20480
	ds_read_b128 v[188:191], v207 offset:21504
	ds_read_b128 v[192:195], v207 offset:22528
	ds_read_b128 v[196:199], v207 offset:23552
	s_add_i32 s34, s34, s13
	s_mov_b32 m0, s34
	v_lshl_add_u64 v[200:201], s[6:7], 0, v[0:1]
	global_load_lds_dwordx4 v[200:201], off
	s_add_i32 m0, s34, 0x2000
	s_add_u32 s46, s6, 0x80000
	v_lshl_add_u64 v[202:203], s[6:7], 0, v[174:175]
	s_addc_u32 s47, s7, 0
	s_add_i32 s34, s35, s13
	global_load_lds_dwordx4 v[202:203], off
	v_lshl_add_u64 v[208:209], s[46:47], 0, v[0:1]
	s_mov_b32 m0, s34
	v_lshl_add_u64 v[210:211], s[94:95], 0, v[174:175]
	global_load_lds_dwordx4 v[208:209], off
	s_add_i32 m0, s34, 0x2000
	v_lshl_add_u64 v[208:209], s[46:47], 0, v[174:175]
	global_load_lds_dwordx4 v[208:209], off
	s_mov_b32 m0, s66
	v_lshl_add_u64 v[208:209], s[94:95], 0, v[0:1]
	global_load_lds_dwordx4 v[208:209], off
	s_mov_b32 m0, s67
	s_nop 0
	global_load_lds_dwordx4 v[210:211], off
	s_setprio 1
	s_waitcnt vmcnt(8) lgkmcnt(0)
	s_barrier
; #define PG8_STAGE(bufoff, gbase, voff) do { _Pragma("unroll") for (int _i = 0; _i < 2; ++_i) \
;         __builtin_amdgcn_global_load_lds((const unsigned*)((const char*)(gbase) + (voff)[_i]), (LAS unsigned*)(lds + (bufoff) + ldsw + _i * 8192), 16, 0, 0); } while (0)
; #define PG8_LDA(dst, b, h) do { _Pragma("unroll") for (int m = 0; m < 4; ++m) _Pragma("unroll") for (int k = 0; k < 2; ++k) dst[m][k] = *(const LAS bf16x8*)(lds + PG8_SA(b, h) + aoff + m * 2048 + k * 1024); } while (0)
; #define PG8_LDB(dst, b, h) do { _Pragma("unroll") for (int n = 0; n < 2; ++n) _Pragma("unroll") for (int k = 0; k < 2; ++k) dst[n][k] = *(const LAS bf16x8*)(lds + PG8_SB(b, h) + boff + n * 2048 + k * 1024); } while (0)
; #define PG8_MMA(ai, bj, At, Bt) do { __builtin_amdgcn_s_setprio(1); _Pragma("unroll") for (int m = 0; m < 4; ++m) _Pragma("unroll") for (int n = 0; n < 2; ++n) _Pragma("unroll") for (int k = 0; k < 2; ++k) \
;         acc[ai][bj][m][n] = __builtin_amdgcn_mfma_f32_16x16x32_bf16(Bt[n][k], At[m][k], acc[ai][bj][m][n], 0, 0, 0); __builtin_amdgcn_s_setprio(0); } while (0)
; #define PG8_WAIT_V(n) asm volatile("s_waitcnt vmcnt(" #n ")" ::: "memory")
; #define PG8_WAIT_L(n) asm volatile("s_waitcnt lgkmcnt(" #n ")" ::: "memory")
; #define PG8_BAR __builtin_amdgcn_s_barrier()
; #define PG8_SCHED __builtin_amdgcn_sched_barrier(0)
; template <class Epi, int AMODE>
; __device__ __forceinline__ void gemm_phase(LAS unsigned char* lds, const Gemm g, const StaticOrder& S, const Epi& E, int stagger_us, int tid_in) {
;     ...
;             PG8_WAIT_V(8); PG8_WAIT_L(0); PG8_BAR; PG8_MMA(1, 0, At, B0); PG8_MMA(1, 1, At, B1); PG8_BAR; PG8_SCHED;
;             PG8_LDB(B0, 1, 0); PG8_LDB(B1, 1, 1); PG8_SCHED; PG8_LDA(At, 1, 0); PG8_STAGE(PG8_SA(0, 1), a2 + hstepA, voffA);
;             PG8_WAIT_V(8); PG8_WAIT_L(0); PG8_BAR; PG8_MMA(0, 0, At, B0); PG8_MMA(0, 1, At, B1); PG8_BAR; PG8_SCHED;
	v_mfma_f32_16x16x32_bf16 v[78:81], v[50:53], v[162:165], v[78:81]
	v_mfma_f32_16x16x32_bf16 v[74:77], v[58:61], v[162:165], v[74:77]
	v_mfma_f32_16x16x32_bf16 v[46:49], v[50:53], v[170:173], v[46:49]
	v_mfma_f32_16x16x32_bf16 v[42:45], v[58:61], v[170:173], v[42:45]
	v_mfma_f32_16x16x32_bf16 v[30:33], v[50:53], v[184:187], v[30:33]
	v_mfma_f32_16x16x32_bf16 v[26:29], v[58:61], v[184:187], v[26:29]
	v_mfma_f32_16x16x32_bf16 v[14:17], v[50:53], v[192:195], v[14:17]
	v_mfma_f32_16x16x32_bf16 v[10:13], v[58:61], v[192:195], v[10:13]
	v_mfma_f32_16x16x32_bf16 v[78:81], v[54:57], v[166:169], v[78:81]
	v_mfma_f32_16x16x32_bf16 v[74:77], v[62:65], v[166:169], v[74:77]
	v_mfma_f32_16x16x32_bf16 v[46:49], v[54:57], v[180:183], v[46:49]
	v_mfma_f32_16x16x32_bf16 v[42:45], v[62:65], v[180:183], v[42:45]
	v_mfma_f32_16x16x32_bf16 v[30:33], v[54:57], v[188:191], v[30:33]
	v_mfma_f32_16x16x32_bf16 v[26:29], v[62:65], v[188:191], v[26:29]
	v_mfma_f32_16x16x32_bf16 v[14:17], v[54:57], v[196:199], v[14:17]
	v_mfma_f32_16x16x32_bf16 v[10:13], v[62:65], v[196:199], v[10:13]
	v_mfma_f32_16x16x32_bf16 v[38:41], v[146:149], v[170:173], v[38:41]
	v_mfma_f32_16x16x32_bf16 v[34:37], v[154:157], v[170:173], v[34:37]
	v_mfma_f32_16x16x32_bf16 v[22:25], v[146:149], v[184:187], v[22:25]
	v_mfma_f32_16x16x32_bf16 v[18:21], v[154:157], v[184:187], v[18:21]
	v_mfma_f32_16x16x32_bf16 v[6:9], v[146:149], v[192:195], v[6:9]
	v_mfma_f32_16x16x32_bf16 v[2:5], v[154:157], v[192:195], v[2:5]
	v_mfma_f32_16x16x32_bf16 v[50:53], v[146:149], v[162:165], v[70:73]
	v_mfma_f32_16x16x32_bf16 v[54:57], v[154:157], v[162:165], v[66:69]
	v_mfma_f32_16x16x32_bf16 v[38:41], v[150:153], v[180:183], v[38:41]
	v_mfma_f32_16x16x32_bf16 v[34:37], v[158:161], v[180:183], v[34:37]
	v_mfma_f32_16x16x32_bf16 v[22:25], v[150:153], v[188:191], v[22:25]
	v_mfma_f32_16x16x32_bf16 v[18:21], v[158:161], v[188:191], v[18:21]
	v_mfma_f32_16x16x32_bf16 v[6:9], v[150:153], v[196:199], v[6:9]
	v_mfma_f32_16x16x32_bf16 v[2:5], v[158:161], v[196:199], v[2:5]
	v_mfma_f32_16x16x32_bf16 v[50:53], v[150:153], v[166:169], v[50:53]
	v_mfma_f32_16x16x32_bf16 v[54:57], v[158:161], v[166:169], v[54:57]
	s_setprio 0
	s_barrier
	s_add_i32 s34, 0, 0x18000
	s_add_i32 s35, 0, 0x1c000
	v_add_u32_e32 v70, s34, v205
	v_add_u32_e32 v158, s35, v205
	ds_read_b128 v[58:61], v70
	ds_read_b128 v[62:65], v70 offset:1024
	ds_read_b128 v[66:69], v70 offset:2048
	ds_read_b128 v[70:73], v70 offset:3072
	ds_read_b128 v[146:149], v158
	ds_read_b128 v[150:153], v158 offset:1024
	ds_read_b128 v[154:157], v158 offset:2048
	ds_read_b128 v[158:161], v158 offset:3072
	ds_read_b128 v[162:165], v207 offset:32768
	ds_read_b128 v[166:169], v207 offset:33792
	ds_read_b128 v[170:173], v207 offset:34816
	ds_read_b128 v[180:183], v207 offset:35840
	ds_read_b128 v[184:187], v207 offset:36864
	ds_read_b128 v[188:191], v207 offset:37888
	ds_read_b128 v[192:195], v207 offset:38912
	ds_read_b128 v[196:199], v207 offset:39936
	s_add_u32 s46, s94, 0x80000
	s_addc_u32 s47, s95, 0
	s_mov_b32 m0, s69
	v_lshl_add_u64 v[212:213], s[46:47], 0, v[0:1]
	global_load_lds_dwordx4 v[212:213], off
	s_mov_b32 m0, s72
	v_lshl_add_u64 v[212:213], s[46:47], 0, v[174:175]
	global_load_lds_dwordx4 v[212:213], off
	s_setprio 1
	s_waitcnt vmcnt(8) lgkmcnt(0)
	s_barrier
	v_mfma_f32_16x16x32_bf16 v[142:145], v[58:61], v[162:165], v[142:145]
	v_mfma_f32_16x16x32_bf16 v[138:141], v[66:69], v[162:165], v[138:141]
	v_mfma_f32_16x16x32_bf16 v[126:129], v[58:61], v[170:173], v[126:129]
	v_mfma_f32_16x16x32_bf16 v[122:125], v[66:69], v[170:173], v[122:125]
	v_mfma_f32_16x16x32_bf16 v[110:113], v[58:61], v[184:187], v[110:113]
	v_mfma_f32_16x16x32_bf16 v[106:109], v[66:69], v[184:187], v[106:109]
	v_mfma_f32_16x16x32_bf16 v[94:97], v[58:61], v[192:195], v[94:97]
	v_mfma_f32_16x16x32_bf16 v[90:93], v[66:69], v[192:195], v[90:93]
	v_mfma_f32_16x16x32_bf16 v[142:145], v[62:65], v[166:169], v[142:145]
	v_mfma_f32_16x16x32_bf16 v[138:141], v[70:73], v[166:169], v[138:141]
	v_mfma_f32_16x16x32_bf16 v[126:129], v[62:65], v[180:183], v[126:129]
	v_mfma_f32_16x16x32_bf16 v[122:125], v[70:73], v[180:183], v[122:125]
	v_mfma_f32_16x16x32_bf16 v[110:113], v[62:65], v[188:191], v[110:113]
	v_mfma_f32_16x16x32_bf16 v[106:109], v[70:73], v[188:191], v[106:109]
	v_mfma_f32_16x16x32_bf16 v[94:97], v[62:65], v[196:199], v[94:97]
	v_mfma_f32_16x16x32_bf16 v[90:93], v[70:73], v[196:199], v[90:93]
	v_mfma_f32_16x16x32_bf16 v[134:137], v[146:149], v[162:165], v[134:137]
	v_mfma_f32_16x16x32_bf16 v[130:133], v[154:157], v[162:165], v[130:133]
	v_mfma_f32_16x16x32_bf16 v[118:121], v[146:149], v[170:173], v[118:121]
	v_mfma_f32_16x16x32_bf16 v[114:117], v[154:157], v[170:173], v[114:117]
	v_mfma_f32_16x16x32_bf16 v[102:105], v[146:149], v[184:187], v[102:105]
	v_mfma_f32_16x16x32_bf16 v[98:101], v[154:157], v[184:187], v[98:101]
	v_mfma_f32_16x16x32_bf16 v[86:89], v[146:149], v[192:195], v[86:89]
	v_mfma_f32_16x16x32_bf16 v[82:85], v[154:157], v[192:195], v[82:85]
	v_mfma_f32_16x16x32_bf16 v[134:137], v[150:153], v[166:169], v[134:137]
	v_mfma_f32_16x16x32_bf16 v[130:133], v[158:161], v[166:169], v[130:133]
	v_mfma_f32_16x16x32_bf16 v[118:121], v[150:153], v[180:183], v[118:121]
	v_mfma_f32_16x16x32_bf16 v[114:117], v[158:161], v[180:183], v[114:117]
	v_mfma_f32_16x16x32_bf16 v[102:105], v[150:153], v[188:191], v[102:105]
	v_mfma_f32_16x16x32_bf16 v[98:101], v[158:161], v[188:191], v[98:101]
	v_mfma_f32_16x16x32_bf16 v[86:89], v[150:153], v[196:199], v[86:89]
	v_mfma_f32_16x16x32_bf16 v[82:85], v[158:161], v[196:199], v[82:85]
	s_setprio 0
	s_barrier
; #define PG8_STAGE(bufoff, gbase, voff) do { _Pragma("unroll") for (int _i = 0; _i < 2; ++_i) \
;         __builtin_amdgcn_global_load_lds((const unsigned*)((const char*)(gbase) + (voff)[_i]), (LAS unsigned*)(lds + (bufoff) + ldsw + _i * 8192), 16, 0, 0); } while (0)
; #define PG8_LDA(dst, b, h) do { _Pragma("unroll") for (int m = 0; m < 4; ++m) _Pragma("unroll") for (int k = 0; k < 2; ++k) dst[m][k] = *(const LAS bf16x8*)(lds + PG8_SA(b, h) + aoff + m * 2048 + k * 1024); } while (0)
; #define PG8_MMA(ai, bj, At, Bt) do { __builtin_amdgcn_s_setprio(1); _Pragma("unroll") for (int m = 0; m < 4; ++m) _Pragma("unroll") for (int n = 0; n < 2; ++n) _Pragma("unroll") for (int k = 0; k < 2; ++k) \
;         acc[ai][bj][m][n] = __builtin_amdgcn_mfma_f32_16x16x32_bf16(Bt[n][k], At[m][k], acc[ai][bj][m][n], 0, 0, 0); __builtin_amdgcn_s_setprio(0); } while (0)
; #define PG8_WAIT_V(n) asm volatile("s_waitcnt vmcnt(" #n ")" ::: "memory")
; #define PG8_WAIT_L(n) asm volatile("s_waitcnt lgkmcnt(" #n ")" ::: "memory")
; #define PG8_BAR __builtin_amdgcn_s_barrier()
; #define PG8_SCHED __builtin_amdgcn_sched_barrier(0)
; template <class Epi, int AMODE>
; __device__ __forceinline__ void gemm_phase(LAS unsigned char* lds, const Gemm g, const StaticOrder& S, const Epi& E, int stagger_us, int tid_in) {
;     ...
;             PG8_LDA(At, 1, 1); PG8_STAGE(PG8_SB(1, 0), b3, voffB); PG8_STAGE(PG8_SB(1, 1), b3 + hstepB, voffB); PG8_STAGE(PG8_SA(1, 0), a3, voffA);
;             PG8_WAIT_V(8); PG8_WAIT_L(0); PG8_BAR; PG8_MMA(1, 0, At, B0); PG8_MMA(1, 1, At, B1); PG8_BAR; PG8_SCHED;
	ds_read_b128 v[162:165], v207 offset:49152
	ds_read_b128 v[166:169], v207 offset:50176
	ds_read_b128 v[170:173], v207 offset:51200
	ds_read_b128 v[180:183], v207 offset:52224
	ds_read_b128 v[184:187], v207 offset:53248
	ds_read_b128 v[188:191], v207 offset:54272
	ds_read_b128 v[192:195], v207 offset:55296
	ds_read_b128 v[196:199], v207 offset:56320
	s_add_i32 s34, s34, s13
	s_mov_b32 m0, s34
	v_lshl_add_u64 v[200:201], v[200:201], 0, s[74:75]
	global_load_lds_dwordx4 v[200:201], off
	s_add_i32 m0, s34, 0x2000
	s_add_u32 s6, s6, 0x80080
	v_lshl_add_u64 v[200:201], v[202:203], 0, s[74:75]
	s_addc_u32 s7, s7, 0
	s_add_i32 s34, s35, s13
	global_load_lds_dwordx4 v[200:201], off
	s_mov_b32 m0, s34
	v_lshl_add_u64 v[200:201], s[6:7], 0, v[0:1]
	global_load_lds_dwordx4 v[200:201], off
	s_add_i32 m0, s34, 0x2000
	v_lshl_add_u64 v[200:201], s[6:7], 0, v[174:175]
	global_load_lds_dwordx4 v[200:201], off
	s_mov_b32 m0, s91
	v_lshl_add_u64 v[200:201], v[208:209], 0, s[74:75]
	global_load_lds_dwordx4 v[200:201], off
	s_mov_b32 m0, s96
	v_lshl_add_u64 v[200:201], v[210:211], 0, s[74:75]
	global_load_lds_dwordx4 v[200:201], off
	s_setprio 1
	s_waitcnt vmcnt(8) lgkmcnt(0)
	s_barrier
	v_mfma_f32_16x16x32_bf16 v[78:81], v[58:61], v[162:165], v[78:81]
	v_mfma_f32_16x16x32_bf16 v[74:77], v[66:69], v[162:165], v[74:77]
	v_mfma_f32_16x16x32_bf16 v[46:49], v[58:61], v[170:173], v[46:49]
	v_mfma_f32_16x16x32_bf16 v[42:45], v[66:69], v[170:173], v[42:45]
	v_mfma_f32_16x16x32_bf16 v[30:33], v[58:61], v[184:187], v[30:33]
	v_mfma_f32_16x16x32_bf16 v[26:29], v[66:69], v[184:187], v[26:29]
	v_mfma_f32_16x16x32_bf16 v[14:17], v[58:61], v[192:195], v[14:17]
	v_mfma_f32_16x16x32_bf16 v[10:13], v[66:69], v[192:195], v[10:13]
	v_mfma_f32_16x16x32_bf16 v[78:81], v[62:65], v[166:169], v[78:81]
	v_mfma_f32_16x16x32_bf16 v[74:77], v[70:73], v[166:169], v[74:77]
	v_mfma_f32_16x16x32_bf16 v[46:49], v[62:65], v[180:183], v[46:49]
	v_mfma_f32_16x16x32_bf16 v[42:45], v[70:73], v[180:183], v[42:45]
	v_mfma_f32_16x16x32_bf16 v[30:33], v[62:65], v[188:191], v[30:33]
	v_mfma_f32_16x16x32_bf16 v[26:29], v[70:73], v[188:191], v[26:29]
	v_mfma_f32_16x16x32_bf16 v[14:17], v[62:65], v[196:199], v[14:17]
	v_mfma_f32_16x16x32_bf16 v[10:13], v[70:73], v[196:199], v[10:13]
	v_mfma_f32_16x16x32_bf16 v[50:53], v[146:149], v[162:165], v[50:53]
	v_mfma_f32_16x16x32_bf16 v[70:73], v[150:153], v[166:169], v[50:53]
	v_mfma_f32_16x16x32_bf16 v[50:53], v[154:157], v[162:165], v[54:57]
	v_mfma_f32_16x16x32_bf16 v[38:41], v[146:149], v[170:173], v[38:41]
	v_mfma_f32_16x16x32_bf16 v[34:37], v[154:157], v[170:173], v[34:37]
	v_mfma_f32_16x16x32_bf16 v[22:25], v[146:149], v[184:187], v[22:25]
	v_mfma_f32_16x16x32_bf16 v[18:21], v[154:157], v[184:187], v[18:21]
	v_mfma_f32_16x16x32_bf16 v[6:9], v[146:149], v[192:195], v[6:9]
	v_mfma_f32_16x16x32_bf16 v[2:5], v[154:157], v[192:195], v[2:5]
	v_mfma_f32_16x16x32_bf16 v[66:69], v[158:161], v[166:169], v[50:53]
	v_mfma_f32_16x16x32_bf16 v[38:41], v[150:153], v[180:183], v[38:41]
	v_mfma_f32_16x16x32_bf16 v[34:37], v[158:161], v[180:183], v[34:37]
	v_mfma_f32_16x16x32_bf16 v[22:25], v[150:153], v[188:191], v[22:25]
	v_mfma_f32_16x16x32_bf16 v[18:21], v[158:161], v[188:191], v[18:21]
	v_mfma_f32_16x16x32_bf16 v[6:9], v[150:153], v[196:199], v[6:9]
	v_mfma_f32_16x16x32_bf16 v[2:5], v[158:161], v[196:199], v[2:5]
	s_setprio 0
	s_barrier
	s_add_i32 s31, s31, 2
	s_add_u32 s29, s29, 0x100
	s_addc_u32 s30, s30, 0
	s_cmp_gt_u32 s31, 29
	s_mov_b64 s[46:47], s[4:5]
	s_cbranch_scc0 .LBB0_1199
	s_and_b64 vcc, exec, s[56:57]
	s_cbranch_vccz .LBB0_1202
	s_barrier

; template <class Epi, int AMODE>
; __device__ __forceinline__ void gemm_phase(LAS unsigned char* lds, const Gemm g, const StaticOrder& S, const Epi& E, int stagger_us, int tid_in) {
;     ...
;             PG8_LDB(B0, 0, 0); PG8_LDB(B1, 0, 1); PG8_SCHED; PG8_LDA(At, 0, 0); PG8_STAGE(PG8_SA(1, 1), a1 + hstepA, voffA);
;             PG8_WAIT_V(8); PG8_WAIT_L(0); PG8_BAR; PG8_MMA(0, 0, At, B0); PG8_MMA(0, 1, At, B1); PG8_BAR; PG8_SCHED;
;             PG8_LDA(At, 0, 1); PG8_STAGE(PG8_SB(0, 0), b2, voffB); PG8_STAGE(PG8_SB(0, 1), b2 + hstepB, voffB); PG8_STAGE(PG8_SA(0, 0), a2, voffA);
;             PG8_WAIT_V(8); PG8_WAIT_L(0); PG8_BAR; PG8_MMA(1, 0, At, B0); PG8_MMA(1, 1, At, B1); PG8_BAR; PG8_SCHED;
;             PG8_LDB(B0, 1, 0); PG8_LDB(B1, 1, 1); PG8_SCHED; PG8_LDA(At, 1, 0); PG8_STAGE(PG8_SA(0, 1), a2 + hstepA, voffA);
;             PG8_WAIT_V(8); PG8_WAIT_L(0); PG8_BAR; PG8_MMA(0, 0, At, B0); PG8_MMA(0, 1, At, B1); PG8_BAR; PG8_SCHED;
;             PG8_LDA(At, 1, 1); PG8_STAGE(PG8_SB(1, 0), b3, voffB); PG8_STAGE(PG8_SB(1, 1), b3 + hstepB, voffB); PG8_STAGE(PG8_SA(1, 0), a3, voffA);
;             PG8_WAIT_V(8); PG8_WAIT_L(0); PG8_BAR; PG8_MMA(1, 0, At, B0); PG8_MMA(1, 1, At, B1); PG8_BAR; PG8_SCHED;
;         }
;         if (wr == 0) PG8_BAR;
;         E(acc, cur, wr, wc, fr, fq);
;         if (!has_next) break;
; #pragma unroll
;         for (int a = 0; a < 2; ++a)
; #pragma unroll
;             for (int b = 0; b < 2; ++b)
; #pragma unroll
;                 for (int m = 0; m < 4; ++m)
; #pragma unroll
;                     for (int n = 0; n < 2; ++n) acc[a][b][m][n] = (f32x4){0.f, 0.f, 0.f, 0.f};
;     __device__ __forceinline__ void operator()(f32x4 (&acc)[2][2][4][2], const Unit& u, int wr, int wc, int fr, int fq) const {
;     ...
;             const int tq = tok0 + 8 * fr; const int tA = tq < 0 ? 0 : (tq > TOK - 1 ? TOK - 1 : tq), tB = (tq + 7) > TOK - 1 ? TOK - 1 : (tq + 7);
;             const int bA = batch_of(tA), bB = batch_of(tB); const bool same = __all(bA == bB);
;             const float* bp0 = bias + 256 * u.pn + 32 * wc + 8 * fq;
;             f32x4 bvA[2][2]; float sq[8];
; #pragma unroll
;             for (int am = 0; am < 8; ++am) { int tok = tq + am; tok = tok < 0 ? 0 : (tok > TOK - 1 ? TOK - 1 : tok); sq[am] = LDG(float, ssq + tok); }
; #pragma unroll
;             for (int bj = 0; bj < 2; ++bj)
; #pragma unroll
.LBB0_1298:
	s_ashr_i32 s47, s46, 31
	s_lshl_b64 s[6:7], s[46:47], 20
	s_add_u32 s96, s9, s6
	s_addc_u32 s97, s72, s7
	s_and_b64 s[6:7], s[42:43], exec
	s_cselect_b32 s27, s97, s5
	s_cselect_b32 s28, s96, s4
	s_add_u32 s29, s4, 0x100
	v_mov_b32_e32 v2, 0
	s_addc_u32 s30, s5, 0
	s_mov_b32 s31, -2
	s_mul_i32 s6, s26, 0xfc
	v_add_u32_e32 v222, s6, v197
	v_med3_i32 v240, v222, 0, v238
	v_add_u32_e32 v241, 0xffffe000, v240
	v_lshrrev_b32_e32 v241, 12, v241
	v_add_u32_e32 v241, 4, v241
	v_lshrrev_b32_e32 v242, 11, v240
	v_mov_b32_e32 v243, 0x2000
	v_cmp_gt_i32_e64 s[6:7], v243, v222
	s_nop 1
	v_cndmask_b32_e64 v241, v241, v242, s[6:7]
	s_lshl_b32 s6, s92, 8
	s_ashr_i32 s7, s6, 31
	v_lshl_add_u64 v[236:237], s[6:7], 2, v[184:185]
	v_mad_u64_u32 v[236:237], s[6:7], v241, s15, v[236:237]
	v_med3_i32 v224, v222, 0, v238
	v_lshlrev_b32_e32 v224, 2, v224
	global_load_dword v224, v224, s[56:57]
	v_add_u32_e32 v228, 1, v222
	v_med3_i32 v228, v228, 0, v238
	v_lshlrev_b32_e32 v228, 2, v228
	global_load_dword v228, v228, s[56:57]
	v_add_u32_e32 v231, 2, v222
	v_med3_i32 v231, v231, 0, v238
	v_lshlrev_b32_e32 v231, 2, v231
	global_load_dword v231, v231, s[56:57]
	v_add_u32_e32 v233, 3, v222
	v_med3_i32 v233, v233, 0, v238
	v_lshlrev_b32_e32 v233, 2, v233
	global_load_dword v233, v233, s[56:57]
	v_add_u32_e32 v234, 4, v222
	v_med3_i32 v234, v234, 0, v238
	v_lshlrev_b32_e32 v234, 2, v234
	global_load_dword v234, v234, s[56:57]
	v_add_u32_e32 v239, 5, v222
	v_med3_i32 v239, v239, 0, v238
	v_lshlrev_b32_e32 v239, 2, v239
	global_load_dword v239, v239, s[56:57]
	v_add_u32_e32 v252, 6, v222
	v_med3_i32 v252, v252, 0, v238
	v_lshlrev_b32_e32 v252, 2, v252
	global_load_dword v252, v252, s[56:57]
	v_add_u32_e32 v253, 7, v222
	v_med3_i32 v253, v253, 0, v238
	v_lshlrev_b32_e32 v253, 2, v253
	global_load_dword v253, v253, s[56:57]
	global_load_dwordx4 v[240:243], v[236:237], off
	global_load_dwordx4 v[244:247], v[236:237], off offset:16
	global_load_dwordx4 v[248:251], v[236:237], off offset:512
	global_load_dwordx2 v[222:223], v[236:237], off offset:528
	s_nop 0
	global_load_dwordx2 v[236:237], v[236:237], off offset:536
	v_mov_b32_e32 v3, v2
	v_mov_b32_e32 v4, v2
	v_mov_b32_e32 v5, v2
	v_mov_b32_e32 v14, v2
	v_mov_b32_e32 v15, v2
	v_mov_b32_e32 v16, v2
	v_mov_b32_e32 v17, v2
	v_mov_b32_e32 v10, v2
	v_mov_b32_e32 v11, v2
	v_mov_b32_e32 v12, v2
	v_mov_b32_e32 v13, v2
	v_mov_b32_e32 v26, v2
	v_mov_b32_e32 v27, v2
	v_mov_b32_e32 v28, v2
	v_mov_b32_e32 v29, v2
	v_mov_b32_e32 v6, v2
	v_mov_b32_e32 v7, v2
	v_mov_b32_e32 v8, v2
	v_mov_b32_e32 v9, v2
	v_mov_b32_e32 v42, v2
	v_mov_b32_e32 v43, v2
	v_mov_b32_e32 v44, v2
	v_mov_b32_e32 v45, v2
	v_mov_b32_e32 v30, v2
	v_mov_b32_e32 v31, v2
	v_mov_b32_e32 v32, v2
	v_mov_b32_e32 v33, v2
	v_mov_b32_e32 v58, v2
	v_mov_b32_e32 v59, v2
	v_mov_b32_e32 v60, v2
	v_mov_b32_e32 v61, v2
	v_mov_b32_e32 v74, v2
	v_mov_b32_e32 v75, v2
	v_mov_b32_e32 v76, v2
	v_mov_b32_e32 v77, v2
	v_mov_b32_e32 v22, v2
	v_mov_b32_e32 v23, v2
	v_mov_b32_e32 v24, v2
	v_mov_b32_e32 v25, v2
	v_mov_b32_e32 v34, v2
	v_mov_b32_e32 v35, v2
	v_mov_b32_e32 v36, v2
	v_mov_b32_e32 v37, v2
	v_mov_b32_e32 v18, v2
	v_mov_b32_e32 v19, v2
	v_mov_b32_e32 v20, v2
	v_mov_b32_e32 v21, v2
	v_mov_b32_e32 v50, v2
	v_mov_b32_e32 v51, v2
	v_mov_b32_e32 v52, v2
	v_mov_b32_e32 v53, v2
	v_mov_b32_e32 v38, v2
	v_mov_b32_e32 v39, v2
	v_mov_b32_e32 v40, v2
	v_mov_b32_e32 v41, v2
	v_mov_b32_e32 v46, v2
	v_mov_b32_e32 v47, v2
	v_mov_b32_e32 v48, v2
	v_mov_b32_e32 v49, v2
	v_mov_b32_e32 v54, v2
	v_mov_b32_e32 v55, v2
	v_mov_b32_e32 v56, v2
	v_mov_b32_e32 v57, v2
	v_mov_b32_e32 v66, v2
	v_mov_b32_e32 v67, v2
	v_mov_b32_e32 v68, v2
	v_mov_b32_e32 v69, v2
	v_mov_b32_e32 v78, v2
	v_mov_b32_e32 v79, v2
	v_mov_b32_e32 v80, v2
	v_mov_b32_e32 v81, v2
	v_mov_b32_e32 v62, v2
	v_mov_b32_e32 v63, v2
	v_mov_b32_e32 v64, v2
	v_mov_b32_e32 v65, v2
	v_mov_b32_e32 v70, v2
	v_mov_b32_e32 v71, v2
	v_mov_b32_e32 v72, v2
	v_mov_b32_e32 v73, v2
	v_mov_b32_e32 v86, v2
	v_mov_b32_e32 v87, v2
	v_mov_b32_e32 v88, v2
	v_mov_b32_e32 v89, v2
	v_mov_b32_e32 v94, v2
	v_mov_b32_e32 v95, v2
	v_mov_b32_e32 v96, v2
	v_mov_b32_e32 v97, v2
	v_mov_b32_e32 v98, v2
	v_mov_b32_e32 v99, v2
	v_mov_b32_e32 v100, v2
	v_mov_b32_e32 v101, v2
	v_mov_b32_e32 v106, v2
	v_mov_b32_e32 v107, v2
	v_mov_b32_e32 v108, v2
	v_mov_b32_e32 v109, v2
	v_mov_b32_e32 v82, v2
	v_mov_b32_e32 v83, v2
	v_mov_b32_e32 v84, v2
	v_mov_b32_e32 v85, v2
	v_mov_b32_e32 v90, v2
	v_mov_b32_e32 v91, v2
	v_mov_b32_e32 v92, v2
	v_mov_b32_e32 v93, v2
	v_mov_b32_e32 v102, v2
	v_mov_b32_e32 v103, v2
	v_mov_b32_e32 v104, v2
	v_mov_b32_e32 v105, v2
	v_mov_b32_e32 v110, v2
	v_mov_b32_e32 v111, v2
	v_mov_b32_e32 v112, v2
	v_mov_b32_e32 v113, v2
	v_mov_b32_e32 v114, v2
	v_mov_b32_e32 v115, v2
	v_mov_b32_e32 v116, v2
	v_mov_b32_e32 v117, v2
	v_mov_b32_e32 v118, v2
	v_mov_b32_e32 v119, v2
	v_mov_b32_e32 v120, v2
	v_mov_b32_e32 v121, v2
	v_mov_b32_e32 v122, v2
	v_mov_b32_e32 v123, v2
	v_mov_b32_e32 v124, v2
	v_mov_b32_e32 v125, v2
	v_mov_b32_e32 v126, v2
	v_mov_b32_e32 v127, v2
	v_mov_b32_e32 v128, v2
	v_mov_b32_e32 v129, v2
	s_add_i32 s34, 0, 0x10000
	s_add_i32 s35, 0, 0x14000
	v_add_u32_e32 v142, s34, v196
	v_add_u32_e32 v158, s35, v196
	ds_read_b128 v[130:133], v142
	ds_read_b128 v[134:137], v142 offset:1024
	ds_read_b128 v[138:141], v142 offset:2048
	ds_read_b128 v[142:145], v142 offset:3072
	ds_read_b128 v[146:149], v158
	ds_read_b128 v[150:153], v158 offset:1024
	ds_read_b128 v[154:157], v158 offset:2048
	ds_read_b128 v[158:161], v158 offset:3072
	ds_read_b128 v[162:165], v201
	ds_read_b128 v[166:169], v201 offset:1024
	ds_read_b128 v[170:173], v201 offset:2048
	ds_read_b128 v[174:177], v201 offset:3072
	ds_read_b128 v[190:193], v201 offset:4096
	ds_read_b128 v[202:205], v201 offset:5120
	ds_read_b128 v[206:209], v201 offset:6144
	ds_read_b128 v[210:213], v201 offset:7168
	s_add_u32 s4, s44, 0x100
	s_addc_u32 s5, s45, 0
	s_cmp_eq_u32 s31, 28
	s_cselect_b32 s43, s95, s5
	s_cselect_b32 s42, s94, s4
	s_cselect_b32 s7, s27, s30
	s_cselect_b32 s6, s28, s29
	s_add_i32 m0, s93, 0xc000
	v_lshl_add_u64 v[194:195], s[44:45], 0, v[186:187]
	global_load_lds_dwordx4 v[194:195], off
	s_add_i32 m0, s93, 0xe000
	v_lshl_add_u64 v[194:195], s[44:45], 0, v[188:189]
	global_load_lds_dwordx4 v[194:195], off
	s_setprio 1
	s_waitcnt lgkmcnt(0)
	s_barrier
; #define PG8_STAGE(bufoff, gbase, voff) do { _Pragma("unroll") for (int _i = 0; _i < 2; ++_i) \
;         __builtin_amdgcn_global_load_lds((const unsigned*)((const char*)(gbase) + (voff)[_i]), (LAS unsigned*)(lds + (bufoff) + ldsw + _i * 8192), 16, 0, 0); } while (0)
; #define PG8_LDA(dst, b, h) do { _Pragma("unroll") for (int m = 0; m < 4; ++m) _Pragma("unroll") for (int k = 0; k < 2; ++k) dst[m][k] = *(const LAS bf16x8*)(lds + PG8_SA(b, h) + aoff + m * 2048 + k * 1024); } while (0)
; #define PG8_LDB(dst, b, h) do { _Pragma("unroll") for (int n = 0; n < 2; ++n) _Pragma("unroll") for (int k = 0; k < 2; ++k) dst[n][k] = *(const LAS bf16x8*)(lds + PG8_SB(b, h) + boff + n * 2048 + k * 1024); } while (0)
; #define PG8_MMA(ai, bj, At, Bt) do { __builtin_amdgcn_s_setprio(1); _Pragma("unroll") for (int m = 0; m < 4; ++m) _Pragma("unroll") for (int n = 0; n < 2; ++n) _Pragma("unroll") for (int k = 0; k < 2; ++k) \
;         acc[ai][bj][m][n] = __builtin_amdgcn_mfma_f32_16x16x32_bf16(Bt[n][k], At[m][k], acc[ai][bj][m][n], 0, 0, 0); __builtin_amdgcn_s_setprio(0); } while (0)
; #define PG8_WAIT_V(n) asm volatile("s_waitcnt vmcnt(" #n ")" ::: "memory")
; #define PG8_WAIT_L(n) asm volatile("s_waitcnt lgkmcnt(" #n ")" ::: "memory")
; #define PG8_BAR __builtin_amdgcn_s_barrier()
; #define PG8_SCHED __builtin_amdgcn_sched_barrier(0)
; template <class Epi, int AMODE>
; __device__ __forceinline__ void gemm_phase(LAS unsigned char* lds, const Gemm g, const StaticOrder& S, const Epi& E, int stagger_us, int tid_in) {
;     ...
;             PG8_LDB(B0, 0, 0); PG8_LDB(B1, 0, 1); PG8_SCHED; PG8_LDA(At, 0, 0); PG8_STAGE(PG8_SA(1, 1), a1 + hstepA, voffA);
;             PG8_WAIT_V(8); PG8_WAIT_L(0); PG8_BAR; PG8_MMA(0, 0, At, B0); PG8_MMA(0, 1, At, B1); PG8_BAR; PG8_SCHED;
;             PG8_LDA(At, 0, 1); PG8_STAGE(PG8_SB(0, 0), b2, voffB); PG8_STAGE(PG8_SB(0, 1), b2 + hstepB, voffB); PG8_STAGE(PG8_SA(0, 0), a2, voffA);
;             PG8_WAIT_V(8); PG8_WAIT_L(0); PG8_BAR; PG8_MMA(1, 0, At, B0); PG8_MMA(1, 1, At, B1); PG8_BAR; PG8_SCHED;
	v_mfma_f32_16x16x32_bf16 v[126:129], v[130:133], v[162:165], v[126:129]
	v_mfma_f32_16x16x32_bf16 v[122:125], v[138:141], v[162:165], v[122:125]
	v_mfma_f32_16x16x32_bf16 v[118:121], v[130:133], v[170:173], v[118:121]
	v_mfma_f32_16x16x32_bf16 v[114:117], v[138:141], v[170:173], v[114:117]
	v_mfma_f32_16x16x32_bf16 v[110:113], v[130:133], v[190:193], v[110:113]
	v_mfma_f32_16x16x32_bf16 v[102:105], v[138:141], v[190:193], v[102:105]
	v_mfma_f32_16x16x32_bf16 v[90:93], v[130:133], v[206:209], v[90:93]
	v_mfma_f32_16x16x32_bf16 v[82:85], v[138:141], v[206:209], v[82:85]
	v_mfma_f32_16x16x32_bf16 v[126:129], v[134:137], v[166:169], v[126:129]
	v_mfma_f32_16x16x32_bf16 v[122:125], v[142:145], v[166:169], v[122:125]
	v_mfma_f32_16x16x32_bf16 v[118:121], v[134:137], v[174:177], v[118:121]
	v_mfma_f32_16x16x32_bf16 v[114:117], v[142:145], v[174:177], v[114:117]
	v_mfma_f32_16x16x32_bf16 v[110:113], v[134:137], v[202:205], v[110:113]
	v_mfma_f32_16x16x32_bf16 v[102:105], v[142:145], v[202:205], v[102:105]
	v_mfma_f32_16x16x32_bf16 v[90:93], v[134:137], v[210:213], v[90:93]
	v_mfma_f32_16x16x32_bf16 v[82:85], v[142:145], v[210:213], v[82:85]
	v_mfma_f32_16x16x32_bf16 v[106:109], v[146:149], v[162:165], v[106:109]
	v_mfma_f32_16x16x32_bf16 v[98:101], v[154:157], v[162:165], v[98:101]
	v_mfma_f32_16x16x32_bf16 v[94:97], v[146:149], v[170:173], v[94:97]
	v_mfma_f32_16x16x32_bf16 v[86:89], v[154:157], v[170:173], v[86:89]
	v_mfma_f32_16x16x32_bf16 v[70:73], v[146:149], v[190:193], v[70:73]
	v_mfma_f32_16x16x32_bf16 v[62:65], v[154:157], v[190:193], v[62:65]
	v_mfma_f32_16x16x32_bf16 v[78:81], v[146:149], v[206:209], v[78:81]
	v_mfma_f32_16x16x32_bf16 v[66:69], v[154:157], v[206:209], v[66:69]
	v_mfma_f32_16x16x32_bf16 v[106:109], v[150:153], v[166:169], v[106:109]
	v_mfma_f32_16x16x32_bf16 v[98:101], v[158:161], v[166:169], v[98:101]
	v_mfma_f32_16x16x32_bf16 v[94:97], v[150:153], v[174:177], v[94:97]
	v_mfma_f32_16x16x32_bf16 v[86:89], v[158:161], v[174:177], v[86:89]
	v_mfma_f32_16x16x32_bf16 v[70:73], v[150:153], v[202:205], v[70:73]
	v_mfma_f32_16x16x32_bf16 v[62:65], v[158:161], v[202:205], v[62:65]
	v_mfma_f32_16x16x32_bf16 v[78:81], v[150:153], v[210:213], v[78:81]
	v_mfma_f32_16x16x32_bf16 v[66:69], v[158:161], v[210:213], v[66:69]
	s_setprio 0
	s_barrier
	ds_read_b128 v[162:165], v201 offset:16384
	ds_read_b128 v[166:169], v201 offset:17408
	ds_read_b128 v[170:173], v201 offset:18432
	ds_read_b128 v[174:177], v201 offset:19456
	ds_read_b128 v[190:193], v201 offset:20480
	ds_read_b128 v[202:205], v201 offset:21504
	ds_read_b128 v[206:209], v201 offset:22528
	ds_read_b128 v[210:213], v201 offset:23552
	s_add_i32 s34, s34, s91
	s_mov_b32 m0, s34
	v_lshl_add_u64 v[194:195], s[6:7], 0, v[0:1]
	global_load_lds_dwordx4 v[194:195], off
	s_add_i32 m0, s34, 0x2000
	s_add_u32 s44, s6, 0x80000
	v_lshl_add_u64 v[214:215], s[6:7], 0, v[182:183]
	s_addc_u32 s45, s7, 0
	s_add_i32 s34, s35, s91
	global_load_lds_dwordx4 v[214:215], off
	v_lshl_add_u64 v[216:217], s[44:45], 0, v[0:1]
	s_mov_b32 m0, s34
	v_lshl_add_u64 v[218:219], s[42:43], 0, v[180:181]
	global_load_lds_dwordx4 v[216:217], off
	s_add_i32 m0, s34, 0x2000
	v_lshl_add_u64 v[216:217], s[44:45], 0, v[182:183]
	global_load_lds_dwordx4 v[216:217], off
	s_mov_b32 m0, s93
	v_lshl_add_u64 v[216:217], s[42:43], 0, v[178:179]
	global_load_lds_dwordx4 v[216:217], off
	s_mov_b32 m0, s83
	s_nop 0
	global_load_lds_dwordx4 v[218:219], off
	s_setprio 1
	s_waitcnt lgkmcnt(0)
	s_barrier
	v_mfma_f32_16x16x32_bf16 v[54:57], v[130:133], v[162:165], v[54:57]
	v_mfma_f32_16x16x32_bf16 v[46:49], v[138:141], v[162:165], v[46:49]
	v_mfma_f32_16x16x32_bf16 v[38:41], v[130:133], v[170:173], v[38:41]
	v_mfma_f32_16x16x32_bf16 v[50:53], v[138:141], v[170:173], v[50:53]
	v_mfma_f32_16x16x32_bf16 v[18:21], v[130:133], v[190:193], v[18:21]
	v_mfma_f32_16x16x32_bf16 v[34:37], v[138:141], v[190:193], v[34:37]
	v_mfma_f32_16x16x32_bf16 v[22:25], v[130:133], v[206:209], v[22:25]
	v_mfma_f32_16x16x32_bf16 v[74:77], v[138:141], v[206:209], v[74:77]
	v_mfma_f32_16x16x32_bf16 v[54:57], v[134:137], v[166:169], v[54:57]
	v_mfma_f32_16x16x32_bf16 v[46:49], v[142:145], v[166:169], v[46:49]
	v_mfma_f32_16x16x32_bf16 v[38:41], v[134:137], v[174:177], v[38:41]
	v_mfma_f32_16x16x32_bf16 v[50:53], v[142:145], v[174:177], v[50:53]
	v_mfma_f32_16x16x32_bf16 v[18:21], v[134:137], v[202:205], v[18:21]
	v_mfma_f32_16x16x32_bf16 v[34:37], v[142:145], v[202:205], v[34:37]
	v_mfma_f32_16x16x32_bf16 v[22:25], v[134:137], v[210:213], v[22:25]
	v_mfma_f32_16x16x32_bf16 v[74:77], v[142:145], v[210:213], v[74:77]
	v_mfma_f32_16x16x32_bf16 v[58:61], v[146:149], v[162:165], v[58:61]
	v_mfma_f32_16x16x32_bf16 v[30:33], v[154:157], v[162:165], v[30:33]
	v_mfma_f32_16x16x32_bf16 v[42:45], v[146:149], v[170:173], v[42:45]
	v_mfma_f32_16x16x32_bf16 v[6:9], v[154:157], v[170:173], v[6:9]
	v_mfma_f32_16x16x32_bf16 v[26:29], v[146:149], v[190:193], v[26:29]
	v_mfma_f32_16x16x32_bf16 v[10:13], v[154:157], v[190:193], v[10:13]
	v_mfma_f32_16x16x32_bf16 v[14:17], v[146:149], v[206:209], v[14:17]
	v_mfma_f32_16x16x32_bf16 v[2:5], v[154:157], v[206:209], v[2:5]
	v_mfma_f32_16x16x32_bf16 v[58:61], v[150:153], v[166:169], v[58:61]
	v_mfma_f32_16x16x32_bf16 v[30:33], v[158:161], v[166:169], v[30:33]
	v_mfma_f32_16x16x32_bf16 v[42:45], v[150:153], v[174:177], v[42:45]
	v_mfma_f32_16x16x32_bf16 v[6:9], v[158:161], v[174:177], v[6:9]
	v_mfma_f32_16x16x32_bf16 v[26:29], v[150:153], v[202:205], v[26:29]
	v_mfma_f32_16x16x32_bf16 v[10:13], v[158:161], v[202:205], v[10:13]
	v_mfma_f32_16x16x32_bf16 v[14:17], v[150:153], v[210:213], v[14:17]
	v_mfma_f32_16x16x32_bf16 v[2:5], v[158:161], v[210:213], v[2:5]
	s_setprio 0
	s_barrier
; #define PG8_STAGE(bufoff, gbase, voff) do { _Pragma("unroll") for (int _i = 0; _i < 2; ++_i) \
;         __builtin_amdgcn_global_load_lds((const unsigned*)((const char*)(gbase) + (voff)[_i]), (LAS unsigned*)(lds + (bufoff) + ldsw + _i * 8192), 16, 0, 0); } while (0)
; #define PG8_LDA(dst, b, h) do { _Pragma("unroll") for (int m = 0; m < 4; ++m) _Pragma("unroll") for (int k = 0; k < 2; ++k) dst[m][k] = *(const LAS bf16x8*)(lds + PG8_SA(b, h) + aoff + m * 2048 + k * 1024); } while (0)
; #define PG8_LDB(dst, b, h) do { _Pragma("unroll") for (int n = 0; n < 2; ++n) _Pragma("unroll") for (int k = 0; k < 2; ++k) dst[n][k] = *(const LAS bf16x8*)(lds + PG8_SB(b, h) + boff + n * 2048 + k * 1024); } while (0)
; #define PG8_MMA(ai, bj, At, Bt) do { __builtin_amdgcn_s_setprio(1); _Pragma("unroll") for (int m = 0; m < 4; ++m) _Pragma("unroll") for (int n = 0; n < 2; ++n) _Pragma("unroll") for (int k = 0; k < 2; ++k) \
;         acc[ai][bj][m][n] = __builtin_amdgcn_mfma_f32_16x16x32_bf16(Bt[n][k], At[m][k], acc[ai][bj][m][n], 0, 0, 0); __builtin_amdgcn_s_setprio(0); } while (0)
; #define PG8_WAIT_V(n) asm volatile("s_waitcnt vmcnt(" #n ")" ::: "memory")
; #define PG8_WAIT_L(n) asm volatile("s_waitcnt lgkmcnt(" #n ")" ::: "memory")
; #define PG8_BAR __builtin_amdgcn_s_barrier()
; #define PG8_SCHED __builtin_amdgcn_sched_barrier(0)
; template <class Epi, int AMODE>
; __device__ __forceinline__ void gemm_phase(LAS unsigned char* lds, const Gemm g, const StaticOrder& S, const Epi& E, int stagger_us, int tid_in) {
;     ...
;             PG8_LDB(B0, 1, 0); PG8_LDB(B1, 1, 1); PG8_SCHED; PG8_LDA(At, 1, 0); PG8_STAGE(PG8_SA(0, 1), a2 + hstepA, voffA);
;             PG8_WAIT_V(8); PG8_WAIT_L(0); PG8_BAR; PG8_MMA(0, 0, At, B0); PG8_MMA(0, 1, At, B1); PG8_BAR; PG8_SCHED;
;             PG8_LDA(At, 1, 1); PG8_STAGE(PG8_SB(1, 0), b3, voffB); PG8_STAGE(PG8_SB(1, 1), b3 + hstepB, voffB); PG8_STAGE(PG8_SA(1, 0), a3, voffA);
;             PG8_WAIT_V(8); PG8_WAIT_L(0); PG8_BAR; PG8_MMA(1, 0, At, B0); PG8_MMA(1, 1, At, B1); PG8_BAR; PG8_SCHED;
	s_add_i32 s34, 0, 0x18000
	s_add_i32 s35, 0, 0x1c000
	v_add_u32_e32 v142, s34, v196
	v_add_u32_e32 v158, s35, v196
	ds_read_b128 v[130:133], v142
	ds_read_b128 v[134:137], v142 offset:1024
	ds_read_b128 v[138:141], v142 offset:2048
	ds_read_b128 v[142:145], v142 offset:3072
	ds_read_b128 v[146:149], v158
	ds_read_b128 v[150:153], v158 offset:1024
	ds_read_b128 v[154:157], v158 offset:2048
	ds_read_b128 v[158:161], v158 offset:3072
	ds_read_b128 v[162:165], v201 offset:32768
	ds_read_b128 v[166:169], v201 offset:33792
	ds_read_b128 v[170:173], v201 offset:34816
	ds_read_b128 v[174:177], v201 offset:35840
	ds_read_b128 v[190:193], v201 offset:36864
	ds_read_b128 v[202:205], v201 offset:37888
	ds_read_b128 v[206:209], v201 offset:38912
	ds_read_b128 v[210:213], v201 offset:39936
	s_add_u32 s42, s42, 0x4000
	s_addc_u32 s43, s43, 0
	s_mov_b32 m0, s79
	v_lshl_add_u64 v[220:221], s[42:43], 0, v[178:179]
	global_load_lds_dwordx4 v[220:221], off
	s_mov_b32 m0, s87
	v_lshl_add_u64 v[220:221], s[42:43], 0, v[180:181]
	global_load_lds_dwordx4 v[220:221], off
	s_setprio 1
	s_waitcnt vmcnt(8) lgkmcnt(0)
	s_barrier
	v_mfma_f32_16x16x32_bf16 v[126:129], v[130:133], v[162:165], v[126:129]
	v_mfma_f32_16x16x32_bf16 v[122:125], v[138:141], v[162:165], v[122:125]
	v_mfma_f32_16x16x32_bf16 v[118:121], v[130:133], v[170:173], v[118:121]
	v_mfma_f32_16x16x32_bf16 v[114:117], v[138:141], v[170:173], v[114:117]
	v_mfma_f32_16x16x32_bf16 v[110:113], v[130:133], v[190:193], v[110:113]
	v_mfma_f32_16x16x32_bf16 v[102:105], v[138:141], v[190:193], v[102:105]
	v_mfma_f32_16x16x32_bf16 v[90:93], v[130:133], v[206:209], v[90:93]
	v_mfma_f32_16x16x32_bf16 v[82:85], v[138:141], v[206:209], v[82:85]
	v_mfma_f32_16x16x32_bf16 v[126:129], v[134:137], v[166:169], v[126:129]
	v_mfma_f32_16x16x32_bf16 v[122:125], v[142:145], v[166:169], v[122:125]
	v_mfma_f32_16x16x32_bf16 v[118:121], v[134:137], v[174:177], v[118:121]
	v_mfma_f32_16x16x32_bf16 v[114:117], v[142:145], v[174:177], v[114:117]
	v_mfma_f32_16x16x32_bf16 v[110:113], v[134:137], v[202:205], v[110:113]
	v_mfma_f32_16x16x32_bf16 v[102:105], v[142:145], v[202:205], v[102:105]
	v_mfma_f32_16x16x32_bf16 v[90:93], v[134:137], v[210:213], v[90:93]
	v_mfma_f32_16x16x32_bf16 v[82:85], v[142:145], v[210:213], v[82:85]
	v_mfma_f32_16x16x32_bf16 v[106:109], v[146:149], v[162:165], v[106:109]
	v_mfma_f32_16x16x32_bf16 v[98:101], v[154:157], v[162:165], v[98:101]
	v_mfma_f32_16x16x32_bf16 v[94:97], v[146:149], v[170:173], v[94:97]
	v_mfma_f32_16x16x32_bf16 v[86:89], v[154:157], v[170:173], v[86:89]
	v_mfma_f32_16x16x32_bf16 v[70:73], v[146:149], v[190:193], v[70:73]
	v_mfma_f32_16x16x32_bf16 v[62:65], v[154:157], v[190:193], v[62:65]
	v_mfma_f32_16x16x32_bf16 v[78:81], v[146:149], v[206:209], v[78:81]
	v_mfma_f32_16x16x32_bf16 v[66:69], v[154:157], v[206:209], v[66:69]
	v_mfma_f32_16x16x32_bf16 v[106:109], v[150:153], v[166:169], v[106:109]
	v_mfma_f32_16x16x32_bf16 v[98:101], v[158:161], v[166:169], v[98:101]
	v_mfma_f32_16x16x32_bf16 v[94:97], v[150:153], v[174:177], v[94:97]
	v_mfma_f32_16x16x32_bf16 v[86:89], v[158:161], v[174:177], v[86:89]
	v_mfma_f32_16x16x32_bf16 v[70:73], v[150:153], v[202:205], v[70:73]
	v_mfma_f32_16x16x32_bf16 v[62:65], v[158:161], v[202:205], v[62:65]
	v_mfma_f32_16x16x32_bf16 v[78:81], v[150:153], v[210:213], v[78:81]
	v_mfma_f32_16x16x32_bf16 v[66:69], v[158:161], v[210:213], v[66:69]
	s_setprio 0
	s_barrier
	ds_read_b128 v[162:165], v201 offset:49152
	ds_read_b128 v[166:169], v201 offset:50176
	ds_read_b128 v[170:173], v201 offset:51200
	ds_read_b128 v[174:177], v201 offset:52224
	ds_read_b128 v[190:193], v201 offset:53248
	ds_read_b128 v[202:205], v201 offset:54272
	ds_read_b128 v[206:209], v201 offset:55296
	ds_read_b128 v[210:213], v201 offset:56320
	s_add_i32 s34, s34, s91
	s_mov_b32 m0, s34
	v_lshl_add_u64 v[194:195], v[194:195], 0, s[74:75]
	global_load_lds_dwordx4 v[194:195], off
	s_add_i32 m0, s34, 0x2000
	s_add_u32 s6, s6, 0x80080
	v_lshl_add_u64 v[194:195], v[214:215], 0, s[74:75]
	s_addc_u32 s7, s7, 0
	s_add_i32 s34, s35, s91
	global_load_lds_dwordx4 v[194:195], off
	s_mov_b32 m0, s34
	v_lshl_add_u64 v[194:195], s[6:7], 0, v[0:1]
	global_load_lds_dwordx4 v[194:195], off
	s_add_i32 m0, s34, 0x2000
	v_lshl_add_u64 v[194:195], s[6:7], 0, v[182:183]
	global_load_lds_dwordx4 v[194:195], off
	s_mov_b32 m0, s67
	v_lshl_add_u64 v[194:195], v[216:217], 0, s[74:75]
	global_load_lds_dwordx4 v[194:195], off
	s_mov_b32 m0, s85
	v_lshl_add_u64 v[194:195], v[218:219], 0, s[74:75]
	global_load_lds_dwordx4 v[194:195], off
	s_setprio 1
	s_waitcnt vmcnt(8) lgkmcnt(0)
	s_barrier
	v_mfma_f32_16x16x32_bf16 v[54:57], v[130:133], v[162:165], v[54:57]
	v_mfma_f32_16x16x32_bf16 v[46:49], v[138:141], v[162:165], v[46:49]
	v_mfma_f32_16x16x32_bf16 v[38:41], v[130:133], v[170:173], v[38:41]
	v_mfma_f32_16x16x32_bf16 v[50:53], v[138:141], v[170:173], v[50:53]
	v_mfma_f32_16x16x32_bf16 v[18:21], v[130:133], v[190:193], v[18:21]
	v_mfma_f32_16x16x32_bf16 v[34:37], v[138:141], v[190:193], v[34:37]
	v_mfma_f32_16x16x32_bf16 v[22:25], v[130:133], v[206:209], v[22:25]
	v_mfma_f32_16x16x32_bf16 v[74:77], v[138:141], v[206:209], v[74:77]
	v_mfma_f32_16x16x32_bf16 v[54:57], v[134:137], v[166:169], v[54:57]
	v_mfma_f32_16x16x32_bf16 v[46:49], v[142:145], v[166:169], v[46:49]
	v_mfma_f32_16x16x32_bf16 v[38:41], v[134:137], v[174:177], v[38:41]
	v_mfma_f32_16x16x32_bf16 v[50:53], v[142:145], v[174:177], v[50:53]
	v_mfma_f32_16x16x32_bf16 v[18:21], v[134:137], v[202:205], v[18:21]
	v_mfma_f32_16x16x32_bf16 v[34:37], v[142:145], v[202:205], v[34:37]
	v_mfma_f32_16x16x32_bf16 v[22:25], v[134:137], v[210:213], v[22:25]
	v_mfma_f32_16x16x32_bf16 v[74:77], v[142:145], v[210:213], v[74:77]
	v_mfma_f32_16x16x32_bf16 v[58:61], v[146:149], v[162:165], v[58:61]
	v_mfma_f32_16x16x32_bf16 v[30:33], v[154:157], v[162:165], v[30:33]
	v_mfma_f32_16x16x32_bf16 v[42:45], v[146:149], v[170:173], v[42:45]
	v_mfma_f32_16x16x32_bf16 v[6:9], v[154:157], v[170:173], v[6:9]
	v_mfma_f32_16x16x32_bf16 v[26:29], v[146:149], v[190:193], v[26:29]
	v_mfma_f32_16x16x32_bf16 v[10:13], v[154:157], v[190:193], v[10:13]
	v_mfma_f32_16x16x32_bf16 v[14:17], v[146:149], v[206:209], v[14:17]
	v_mfma_f32_16x16x32_bf16 v[2:5], v[154:157], v[206:209], v[2:5]
	v_mfma_f32_16x16x32_bf16 v[58:61], v[150:153], v[166:169], v[58:61]
	v_mfma_f32_16x16x32_bf16 v[30:33], v[158:161], v[166:169], v[30:33]
	v_mfma_f32_16x16x32_bf16 v[42:45], v[150:153], v[174:177], v[42:45]
	v_mfma_f32_16x16x32_bf16 v[6:9], v[158:161], v[174:177], v[6:9]
	v_mfma_f32_16x16x32_bf16 v[26:29], v[150:153], v[202:205], v[26:29]
	v_mfma_f32_16x16x32_bf16 v[10:13], v[158:161], v[202:205], v[10:13]
	v_mfma_f32_16x16x32_bf16 v[14:17], v[150:153], v[210:213], v[14:17]
	v_mfma_f32_16x16x32_bf16 v[2:5], v[158:161], v[210:213], v[2:5]
	s_setprio 0
	s_barrier
	s_add_i32 s31, s31, 2
	s_add_u32 s29, s29, 0x100
	s_addc_u32 s30, s30, 0
	s_cmp_gt_u32 s31, 29
	s_mov_b64 s[44:45], s[4:5]
; #define PG8_STAGE(bufoff, gbase, voff) do { _Pragma("unroll") for (int _i = 0; _i < 2; ++_i) \
;         __builtin_amdgcn_global_load_lds((const unsigned*)((const char*)(gbase) + (voff)[_i]), (LAS unsigned*)(lds + (bufoff) + ldsw + _i * 8192), 16, 0, 0); } while (0)
; #define PG8_LDA(dst, b, h) do { _Pragma("unroll") for (int m = 0; m < 4; ++m) _Pragma("unroll") for (int k = 0; k < 2; ++k) dst[m][k] = *(const LAS bf16x8*)(lds + PG8_SA(b, h) + aoff + m * 2048 + k * 1024); } while (0)
; #define PG8_LDB(dst, b, h) do { _Pragma("unroll") for (int n = 0; n < 2; ++n) _Pragma("unroll") for (int k = 0; k < 2; ++k) dst[n][k] = *(const LAS bf16x8*)(lds + PG8_SB(b, h) + boff + n * 2048 + k * 1024); } while (0)
; #define PG8_MMA(ai, bj, At, Bt) do { __builtin_amdgcn_s_setprio(1); _Pragma("unroll") for (int m = 0; m < 4; ++m) _Pragma("unroll") for (int n = 0; n < 2; ++n) _Pragma("unroll") for (int k = 0; k < 2; ++k) \
;         acc[ai][bj][m][n] = __builtin_amdgcn_mfma_f32_16x16x32_bf16(Bt[n][k], At[m][k], acc[ai][bj][m][n], 0, 0, 0); __builtin_amdgcn_s_setprio(0); } while (0)
; #define PG8_WAIT_V(n) asm volatile("s_waitcnt vmcnt(" #n ")" ::: "memory")
; #define PG8_WAIT_L(n) asm volatile("s_waitcnt lgkmcnt(" #n ")" ::: "memory")
; #define PG8_BAR __builtin_amdgcn_s_barrier()
; #define PG8_SCHED __builtin_amdgcn_sched_barrier(0)
; template <class Epi, int AMODE>
; __device__ __forceinline__ void gemm_phase(LAS unsigned char* lds, const Gemm g, const StaticOrder& S, const Epi& E, int stagger_us, int tid_in) {
;     ...
;             PG8_LDB(B0, 0, 0); PG8_LDB(B1, 0, 1); PG8_SCHED; PG8_LDA(At, 0, 0); PG8_STAGE(PG8_SA(1, 1), a1 + hstepA, voffA);
;             PG8_WAIT_V(8); PG8_WAIT_L(0); PG8_BAR; PG8_MMA(0, 0, At, B0); PG8_MMA(0, 1, At, B1); PG8_BAR; PG8_SCHED;
;             PG8_LDA(At, 0, 1); PG8_STAGE(PG8_SB(0, 0), b2, voffB); PG8_STAGE(PG8_SB(0, 1), b2 + hstepB, voffB); PG8_STAGE(PG8_SA(0, 0), a2, voffA);
;             PG8_WAIT_V(8); PG8_WAIT_L(0); PG8_BAR; PG8_MMA(1, 0, At, B0); PG8_MMA(1, 1, At, B1); PG8_BAR; PG8_SCHED;
.LBB0_1299:
	s_add_i32 s34, 0, 0x10000
	s_add_i32 s35, 0, 0x14000
	v_add_u32_e32 v142, s34, v196
	v_add_u32_e32 v158, s35, v196
	ds_read_b128 v[130:133], v142
	ds_read_b128 v[134:137], v142 offset:1024
	ds_read_b128 v[138:141], v142 offset:2048
	ds_read_b128 v[142:145], v142 offset:3072
	ds_read_b128 v[146:149], v158
	ds_read_b128 v[150:153], v158 offset:1024
	ds_read_b128 v[154:157], v158 offset:2048
	ds_read_b128 v[158:161], v158 offset:3072
	ds_read_b128 v[162:165], v201
	ds_read_b128 v[166:169], v201 offset:1024
	ds_read_b128 v[170:173], v201 offset:2048
	ds_read_b128 v[174:177], v201 offset:3072
	ds_read_b128 v[190:193], v201 offset:4096
	ds_read_b128 v[202:205], v201 offset:5120
	ds_read_b128 v[206:209], v201 offset:6144
	ds_read_b128 v[210:213], v201 offset:7168
	s_add_u32 s4, s44, 0x100
	s_addc_u32 s5, s45, 0
	s_cmp_eq_u32 s31, 28
	s_cselect_b32 s43, s95, s5
	s_cselect_b32 s42, s94, s4
	s_cselect_b32 s7, s27, s30
	s_cselect_b32 s6, s28, s29
	s_add_i32 m0, s93, 0xc000
	v_lshl_add_u64 v[194:195], s[44:45], 0, v[186:187]
	global_load_lds_dwordx4 v[194:195], off
	s_add_i32 m0, s93, 0xe000
	v_lshl_add_u64 v[194:195], s[44:45], 0, v[188:189]
	global_load_lds_dwordx4 v[194:195], off
	s_setprio 1
	s_waitcnt vmcnt(8) lgkmcnt(0)
	s_barrier
	v_mfma_f32_16x16x32_bf16 v[126:129], v[130:133], v[162:165], v[126:129]
	v_mfma_f32_16x16x32_bf16 v[122:125], v[138:141], v[162:165], v[122:125]
	v_mfma_f32_16x16x32_bf16 v[118:121], v[130:133], v[170:173], v[118:121]
	v_mfma_f32_16x16x32_bf16 v[114:117], v[138:141], v[170:173], v[114:117]
	v_mfma_f32_16x16x32_bf16 v[110:113], v[130:133], v[190:193], v[110:113]
	v_mfma_f32_16x16x32_bf16 v[102:105], v[138:141], v[190:193], v[102:105]
	v_mfma_f32_16x16x32_bf16 v[90:93], v[130:133], v[206:209], v[90:93]
	v_mfma_f32_16x16x32_bf16 v[82:85], v[138:141], v[206:209], v[82:85]
	v_mfma_f32_16x16x32_bf16 v[126:129], v[134:137], v[166:169], v[126:129]
	v_mfma_f32_16x16x32_bf16 v[122:125], v[142:145], v[166:169], v[122:125]
	v_mfma_f32_16x16x32_bf16 v[118:121], v[134:137], v[174:177], v[118:121]
	v_mfma_f32_16x16x32_bf16 v[114:117], v[142:145], v[174:177], v[114:117]
	v_mfma_f32_16x16x32_bf16 v[110:113], v[134:137], v[202:205], v[110:113]
	v_mfma_f32_16x16x32_bf16 v[102:105], v[142:145], v[202:205], v[102:105]
	v_mfma_f32_16x16x32_bf16 v[90:93], v[134:137], v[210:213], v[90:93]
	v_mfma_f32_16x16x32_bf16 v[82:85], v[142:145], v[210:213], v[82:85]
	v_mfma_f32_16x16x32_bf16 v[106:109], v[146:149], v[162:165], v[106:109]
	v_mfma_f32_16x16x32_bf16 v[98:101], v[154:157], v[162:165], v[98:101]
	v_mfma_f32_16x16x32_bf16 v[94:97], v[146:149], v[170:173], v[94:97]
	v_mfma_f32_16x16x32_bf16 v[86:89], v[154:157], v[170:173], v[86:89]
	v_mfma_f32_16x16x32_bf16 v[70:73], v[146:149], v[190:193], v[70:73]
	v_mfma_f32_16x16x32_bf16 v[62:65], v[154:157], v[190:193], v[62:65]
	v_mfma_f32_16x16x32_bf16 v[78:81], v[146:149], v[206:209], v[78:81]
	v_mfma_f32_16x16x32_bf16 v[66:69], v[154:157], v[206:209], v[66:69]
	v_mfma_f32_16x16x32_bf16 v[106:109], v[150:153], v[166:169], v[106:109]
	v_mfma_f32_16x16x32_bf16 v[98:101], v[158:161], v[166:169], v[98:101]
	v_mfma_f32_16x16x32_bf16 v[94:97], v[150:153], v[174:177], v[94:97]
	v_mfma_f32_16x16x32_bf16 v[86:89], v[158:161], v[174:177], v[86:89]
	v_mfma_f32_16x16x32_bf16 v[70:73], v[150:153], v[202:205], v[70:73]
	v_mfma_f32_16x16x32_bf16 v[62:65], v[158:161], v[202:205], v[62:65]
	v_mfma_f32_16x16x32_bf16 v[78:81], v[150:153], v[210:213], v[78:81]
	v_mfma_f32_16x16x32_bf16 v[66:69], v[158:161], v[210:213], v[66:69]
	s_setprio 0
	s_barrier
	ds_read_b128 v[162:165], v201 offset:16384
	ds_read_b128 v[166:169], v201 offset:17408
	ds_read_b128 v[170:173], v201 offset:18432
	ds_read_b128 v[174:177], v201 offset:19456
	ds_read_b128 v[190:193], v201 offset:20480
	ds_read_b128 v[202:205], v201 offset:21504
	ds_read_b128 v[206:209], v201 offset:22528
	ds_read_b128 v[210:213], v201 offset:23552
	s_add_i32 s34, s34, s91
	s_mov_b32 m0, s34
	v_lshl_add_u64 v[194:195], s[6:7], 0, v[0:1]
	global_load_lds_dwordx4 v[194:195], off
	s_add_i32 m0, s34, 0x2000
	s_add_u32 s44, s6, 0x80000
	v_lshl_add_u64 v[214:215], s[6:7], 0, v[182:183]
	s_addc_u32 s45, s7, 0
	s_add_i32 s34, s35, s91
	global_load_lds_dwordx4 v[214:215], off
	v_lshl_add_u64 v[216:217], s[44:45], 0, v[0:1]
	s_mov_b32 m0, s34
	v_lshl_add_u64 v[218:219], s[42:43], 0, v[180:181]
	global_load_lds_dwordx4 v[216:217], off
	s_add_i32 m0, s34, 0x2000
	v_lshl_add_u64 v[216:217], s[44:45], 0, v[182:183]
	global_load_lds_dwordx4 v[216:217], off
	s_mov_b32 m0, s93
	v_lshl_add_u64 v[216:217], s[42:43], 0, v[178:179]
	global_load_lds_dwordx4 v[216:217], off
	s_mov_b32 m0, s83
	s_nop 0
	global_load_lds_dwordx4 v[218:219], off
	s_setprio 1
	s_waitcnt vmcnt(8) lgkmcnt(0)
	s_barrier
; #define PG8_STAGE(bufoff, gbase, voff) do { _Pragma("unroll") for (int _i = 0; _i < 2; ++_i) \
;         __builtin_amdgcn_global_load_lds((const unsigned*)((const char*)(gbase) + (voff)[_i]), (LAS unsigned*)(lds + (bufoff) + ldsw + _i * 8192), 16, 0, 0); } while (0)
; #define PG8_LDA(dst, b, h) do { _Pragma("unroll") for (int m = 0; m < 4; ++m) _Pragma("unroll") for (int k = 0; k < 2; ++k) dst[m][k] = *(const LAS bf16x8*)(lds + PG8_SA(b, h) + aoff + m * 2048 + k * 1024); } while (0)
; #define PG8_LDB(dst, b, h) do { _Pragma("unroll") for (int n = 0; n < 2; ++n) _Pragma("unroll") for (int k = 0; k < 2; ++k) dst[n][k] = *(const LAS bf16x8*)(lds + PG8_SB(b, h) + boff + n * 2048 + k * 1024); } while (0)
; #define PG8_MMA(ai, bj, At, Bt) do { __builtin_amdgcn_s_setprio(1); _Pragma("unroll") for (int m = 0; m < 4; ++m) _Pragma("unroll") for (int n = 0; n < 2; ++n) _Pragma("unroll") for (int k = 0; k < 2; ++k) \
;         acc[ai][bj][m][n] = __builtin_amdgcn_mfma_f32_16x16x32_bf16(Bt[n][k], At[m][k], acc[ai][bj][m][n], 0, 0, 0); __builtin_amdgcn_s_setprio(0); } while (0)
; #define PG8_WAIT_V(n) asm volatile("s_waitcnt vmcnt(" #n ")" ::: "memory")
; #define PG8_WAIT_L(n) asm volatile("s_waitcnt lgkmcnt(" #n ")" ::: "memory")
; #define PG8_BAR __builtin_amdgcn_s_barrier()
; #define PG8_SCHED __builtin_amdgcn_sched_barrier(0)
; template <class Epi, int AMODE>
; __device__ __forceinline__ void gemm_phase(LAS unsigned char* lds, const Gemm g, const StaticOrder& S, const Epi& E, int stagger_us, int tid_in) {
;     ...
;             PG8_WAIT_V(8); PG8_WAIT_L(0); PG8_BAR; PG8_MMA(1, 0, At, B0); PG8_MMA(1, 1, At, B1); PG8_BAR; PG8_SCHED;
;             PG8_LDB(B0, 1, 0); PG8_LDB(B1, 1, 1); PG8_SCHED; PG8_LDA(At, 1, 0); PG8_STAGE(PG8_SA(0, 1), a2 + hstepA, voffA);
;             PG8_WAIT_V(8); PG8_WAIT_L(0); PG8_BAR; PG8_MMA(0, 0, At, B0); PG8_MMA(0, 1, At, B1); PG8_BAR; PG8_SCHED;
	v_mfma_f32_16x16x32_bf16 v[54:57], v[130:133], v[162:165], v[54:57]
	v_mfma_f32_16x16x32_bf16 v[46:49], v[138:141], v[162:165], v[46:49]
	v_mfma_f32_16x16x32_bf16 v[38:41], v[130:133], v[170:173], v[38:41]
	v_mfma_f32_16x16x32_bf16 v[50:53], v[138:141], v[170:173], v[50:53]
	v_mfma_f32_16x16x32_bf16 v[18:21], v[130:133], v[190:193], v[18:21]
	v_mfma_f32_16x16x32_bf16 v[34:37], v[138:141], v[190:193], v[34:37]
	v_mfma_f32_16x16x32_bf16 v[22:25], v[130:133], v[206:209], v[22:25]
	v_mfma_f32_16x16x32_bf16 v[74:77], v[138:141], v[206:209], v[74:77]
	v_mfma_f32_16x16x32_bf16 v[54:57], v[134:137], v[166:169], v[54:57]
	v_mfma_f32_16x16x32_bf16 v[46:49], v[142:145], v[166:169], v[46:49]
	v_mfma_f32_16x16x32_bf16 v[38:41], v[134:137], v[174:177], v[38:41]
	v_mfma_f32_16x16x32_bf16 v[50:53], v[142:145], v[174:177], v[50:53]
	v_mfma_f32_16x16x32_bf16 v[18:21], v[134:137], v[202:205], v[18:21]
	v_mfma_f32_16x16x32_bf16 v[34:37], v[142:145], v[202:205], v[34:37]
	v_mfma_f32_16x16x32_bf16 v[22:25], v[134:137], v[210:213], v[22:25]
	v_mfma_f32_16x16x32_bf16 v[74:77], v[142:145], v[210:213], v[74:77]
	v_mfma_f32_16x16x32_bf16 v[58:61], v[146:149], v[162:165], v[58:61]
	v_mfma_f32_16x16x32_bf16 v[30:33], v[154:157], v[162:165], v[30:33]
	v_mfma_f32_16x16x32_bf16 v[42:45], v[146:149], v[170:173], v[42:45]
	v_mfma_f32_16x16x32_bf16 v[6:9], v[154:157], v[170:173], v[6:9]
	v_mfma_f32_16x16x32_bf16 v[26:29], v[146:149], v[190:193], v[26:29]
	v_mfma_f32_16x16x32_bf16 v[10:13], v[154:157], v[190:193], v[10:13]
	v_mfma_f32_16x16x32_bf16 v[14:17], v[146:149], v[206:209], v[14:17]
	v_mfma_f32_16x16x32_bf16 v[2:5], v[154:157], v[206:209], v[2:5]
	v_mfma_f32_16x16x32_bf16 v[58:61], v[150:153], v[166:169], v[58:61]
	v_mfma_f32_16x16x32_bf16 v[30:33], v[158:161], v[166:169], v[30:33]
	v_mfma_f32_16x16x32_bf16 v[42:45], v[150:153], v[174:177], v[42:45]
	v_mfma_f32_16x16x32_bf16 v[6:9], v[158:161], v[174:177], v[6:9]
	v_mfma_f32_16x16x32_bf16 v[26:29], v[150:153], v[202:205], v[26:29]
	v_mfma_f32_16x16x32_bf16 v[10:13], v[158:161], v[202:205], v[10:13]
	v_mfma_f32_16x16x32_bf16 v[14:17], v[150:153], v[210:213], v[14:17]
	v_mfma_f32_16x16x32_bf16 v[2:5], v[158:161], v[210:213], v[2:5]
	s_setprio 0
	s_barrier
	s_add_i32 s34, 0, 0x18000
	s_add_i32 s35, 0, 0x1c000
	v_add_u32_e32 v142, s34, v196
	v_add_u32_e32 v158, s35, v196
	ds_read_b128 v[130:133], v142
	ds_read_b128 v[134:137], v142 offset:1024
	ds_read_b128 v[138:141], v142 offset:2048
	ds_read_b128 v[142:145], v142 offset:3072
	ds_read_b128 v[146:149], v158
	ds_read_b128 v[150:153], v158 offset:1024
	ds_read_b128 v[154:157], v158 offset:2048
	ds_read_b128 v[158:161], v158 offset:3072
	ds_read_b128 v[162:165], v201 offset:32768
	ds_read_b128 v[166:169], v201 offset:33792
	ds_read_b128 v[170:173], v201 offset:34816
	ds_read_b128 v[174:177], v201 offset:35840
	ds_read_b128 v[190:193], v201 offset:36864
	ds_read_b128 v[202:205], v201 offset:37888
	ds_read_b128 v[206:209], v201 offset:38912
	ds_read_b128 v[210:213], v201 offset:39936
	s_add_u32 s42, s42, 0x4000
	s_addc_u32 s43, s43, 0
	s_mov_b32 m0, s79
	v_lshl_add_u64 v[220:221], s[42:43], 0, v[178:179]
	global_load_lds_dwordx4 v[220:221], off
	s_mov_b32 m0, s87
	v_lshl_add_u64 v[220:221], s[42:43], 0, v[180:181]
	global_load_lds_dwordx4 v[220:221], off
	s_setprio 1
	s_waitcnt vmcnt(8) lgkmcnt(0)
	s_barrier
	v_mfma_f32_16x16x32_bf16 v[126:129], v[130:133], v[162:165], v[126:129]
	v_mfma_f32_16x16x32_bf16 v[122:125], v[138:141], v[162:165], v[122:125]
	v_mfma_f32_16x16x32_bf16 v[118:121], v[130:133], v[170:173], v[118:121]
	v_mfma_f32_16x16x32_bf16 v[114:117], v[138:141], v[170:173], v[114:117]
	v_mfma_f32_16x16x32_bf16 v[110:113], v[130:133], v[190:193], v[110:113]
	v_mfma_f32_16x16x32_bf16 v[102:105], v[138:141], v[190:193], v[102:105]
	v_mfma_f32_16x16x32_bf16 v[90:93], v[130:133], v[206:209], v[90:93]
	v_mfma_f32_16x16x32_bf16 v[82:85], v[138:141], v[206:209], v[82:85]
	v_mfma_f32_16x16x32_bf16 v[126:129], v[134:137], v[166:169], v[126:129]
	v_mfma_f32_16x16x32_bf16 v[122:125], v[142:145], v[166:169], v[122:125]
	v_mfma_f32_16x16x32_bf16 v[118:121], v[134:137], v[174:177], v[118:121]
	v_mfma_f32_16x16x32_bf16 v[114:117], v[142:145], v[174:177], v[114:117]
	v_mfma_f32_16x16x32_bf16 v[110:113], v[134:137], v[202:205], v[110:113]
	v_mfma_f32_16x16x32_bf16 v[102:105], v[142:145], v[202:205], v[102:105]
	v_mfma_f32_16x16x32_bf16 v[90:93], v[134:137], v[210:213], v[90:93]
	v_mfma_f32_16x16x32_bf16 v[82:85], v[142:145], v[210:213], v[82:85]
	v_mfma_f32_16x16x32_bf16 v[106:109], v[146:149], v[162:165], v[106:109]
	v_mfma_f32_16x16x32_bf16 v[98:101], v[154:157], v[162:165], v[98:101]
	v_mfma_f32_16x16x32_bf16 v[94:97], v[146:149], v[170:173], v[94:97]
	v_mfma_f32_16x16x32_bf16 v[86:89], v[154:157], v[170:173], v[86:89]
	v_mfma_f32_16x16x32_bf16 v[70:73], v[146:149], v[190:193], v[70:73]
	v_mfma_f32_16x16x32_bf16 v[62:65], v[154:157], v[190:193], v[62:65]
	v_mfma_f32_16x16x32_bf16 v[78:81], v[146:149], v[206:209], v[78:81]
	v_mfma_f32_16x16x32_bf16 v[66:69], v[154:157], v[206:209], v[66:69]
	v_mfma_f32_16x16x32_bf16 v[106:109], v[150:153], v[166:169], v[106:109]
	v_mfma_f32_16x16x32_bf16 v[98:101], v[158:161], v[166:169], v[98:101]
	v_mfma_f32_16x16x32_bf16 v[94:97], v[150:153], v[174:177], v[94:97]
	v_mfma_f32_16x16x32_bf16 v[86:89], v[158:161], v[174:177], v[86:89]
	v_mfma_f32_16x16x32_bf16 v[70:73], v[150:153], v[202:205], v[70:73]
	v_mfma_f32_16x16x32_bf16 v[62:65], v[158:161], v[202:205], v[62:65]
	v_mfma_f32_16x16x32_bf16 v[78:81], v[150:153], v[210:213], v[78:81]
	v_mfma_f32_16x16x32_bf16 v[66:69], v[158:161], v[210:213], v[66:69]
	s_setprio 0
	s_barrier
; #define PG8_STAGE(bufoff, gbase, voff) do { _Pragma("unroll") for (int _i = 0; _i < 2; ++_i) \
;         __builtin_amdgcn_global_load_lds((const unsigned*)((const char*)(gbase) + (voff)[_i]), (LAS unsigned*)(lds + (bufoff) + ldsw + _i * 8192), 16, 0, 0); } while (0)
; #define PG8_LDA(dst, b, h) do { _Pragma("unroll") for (int m = 0; m < 4; ++m) _Pragma("unroll") for (int k = 0; k < 2; ++k) dst[m][k] = *(const LAS bf16x8*)(lds + PG8_SA(b, h) + aoff + m * 2048 + k * 1024); } while (0)
; #define PG8_MMA(ai, bj, At, Bt) do { __builtin_amdgcn_s_setprio(1); _Pragma("unroll") for (int m = 0; m < 4; ++m) _Pragma("unroll") for (int n = 0; n < 2; ++n) _Pragma("unroll") for (int k = 0; k < 2; ++k) \
;         acc[ai][bj][m][n] = __builtin_amdgcn_mfma_f32_16x16x32_bf16(Bt[n][k], At[m][k], acc[ai][bj][m][n], 0, 0, 0); __builtin_amdgcn_s_setprio(0); } while (0)
; #define PG8_WAIT_V(n) asm volatile("s_waitcnt vmcnt(" #n ")" ::: "memory")
; #define PG8_WAIT_L(n) asm volatile("s_waitcnt lgkmcnt(" #n ")" ::: "memory")
; #define PG8_BAR __builtin_amdgcn_s_barrier()
; #define PG8_SCHED __builtin_amdgcn_sched_barrier(0)
; template <class Epi, int AMODE>
; __device__ __forceinline__ void gemm_phase(LAS unsigned char* lds, const Gemm g, const StaticOrder& S, const Epi& E, int stagger_us, int tid_in) {
;     ...
;             PG8_LDA(At, 1, 1); PG8_STAGE(PG8_SB(1, 0), b3, voffB); PG8_STAGE(PG8_SB(1, 1), b3 + hstepB, voffB); PG8_STAGE(PG8_SA(1, 0), a3, voffA);
;             PG8_WAIT_V(8); PG8_WAIT_L(0); PG8_BAR; PG8_MMA(1, 0, At, B0); PG8_MMA(1, 1, At, B1); PG8_BAR; PG8_SCHED;
;         }
;         if (wr == 0) PG8_BAR;
	ds_read_b128 v[162:165], v201 offset:49152
	ds_read_b128 v[166:169], v201 offset:50176
	ds_read_b128 v[170:173], v201 offset:51200
	ds_read_b128 v[174:177], v201 offset:52224
	ds_read_b128 v[190:193], v201 offset:53248
	ds_read_b128 v[202:205], v201 offset:54272
	ds_read_b128 v[206:209], v201 offset:55296
	ds_read_b128 v[210:213], v201 offset:56320
	s_add_i32 s34, s34, s91
	s_mov_b32 m0, s34
	v_lshl_add_u64 v[194:195], v[194:195], 0, s[74:75]
	global_load_lds_dwordx4 v[194:195], off
	s_add_i32 m0, s34, 0x2000
	s_add_u32 s6, s6, 0x80080
	v_lshl_add_u64 v[194:195], v[214:215], 0, s[74:75]
	s_addc_u32 s7, s7, 0
	s_add_i32 s34, s35, s91
	global_load_lds_dwordx4 v[194:195], off
	s_mov_b32 m0, s34
	v_lshl_add_u64 v[194:195], s[6:7], 0, v[0:1]
	global_load_lds_dwordx4 v[194:195], off
	s_add_i32 m0, s34, 0x2000
	v_lshl_add_u64 v[194:195], s[6:7], 0, v[182:183]
	global_load_lds_dwordx4 v[194:195], off
	s_mov_b32 m0, s67
	v_lshl_add_u64 v[194:195], v[216:217], 0, s[74:75]
	global_load_lds_dwordx4 v[194:195], off
	s_mov_b32 m0, s85
	v_lshl_add_u64 v[194:195], v[218:219], 0, s[74:75]
	global_load_lds_dwordx4 v[194:195], off
	s_setprio 1
	s_waitcnt vmcnt(8) lgkmcnt(0)
	s_barrier
	v_mfma_f32_16x16x32_bf16 v[54:57], v[130:133], v[162:165], v[54:57]
	v_mfma_f32_16x16x32_bf16 v[46:49], v[138:141], v[162:165], v[46:49]
	v_mfma_f32_16x16x32_bf16 v[38:41], v[130:133], v[170:173], v[38:41]
	v_mfma_f32_16x16x32_bf16 v[50:53], v[138:141], v[170:173], v[50:53]
	v_mfma_f32_16x16x32_bf16 v[18:21], v[130:133], v[190:193], v[18:21]
	v_mfma_f32_16x16x32_bf16 v[34:37], v[138:141], v[190:193], v[34:37]
	v_mfma_f32_16x16x32_bf16 v[22:25], v[130:133], v[206:209], v[22:25]
	v_mfma_f32_16x16x32_bf16 v[74:77], v[138:141], v[206:209], v[74:77]
	v_mfma_f32_16x16x32_bf16 v[54:57], v[134:137], v[166:169], v[54:57]
	v_mfma_f32_16x16x32_bf16 v[46:49], v[142:145], v[166:169], v[46:49]
	v_mfma_f32_16x16x32_bf16 v[38:41], v[134:137], v[174:177], v[38:41]
	v_mfma_f32_16x16x32_bf16 v[50:53], v[142:145], v[174:177], v[50:53]
	v_mfma_f32_16x16x32_bf16 v[18:21], v[134:137], v[202:205], v[18:21]
	v_mfma_f32_16x16x32_bf16 v[34:37], v[142:145], v[202:205], v[34:37]
	v_mfma_f32_16x16x32_bf16 v[22:25], v[134:137], v[210:213], v[22:25]
	v_mfma_f32_16x16x32_bf16 v[74:77], v[142:145], v[210:213], v[74:77]
	v_mfma_f32_16x16x32_bf16 v[58:61], v[146:149], v[162:165], v[58:61]
	v_mfma_f32_16x16x32_bf16 v[30:33], v[154:157], v[162:165], v[30:33]
	v_mfma_f32_16x16x32_bf16 v[42:45], v[146:149], v[170:173], v[42:45]
	v_mfma_f32_16x16x32_bf16 v[6:9], v[154:157], v[170:173], v[6:9]
	v_mfma_f32_16x16x32_bf16 v[26:29], v[146:149], v[190:193], v[26:29]
	v_mfma_f32_16x16x32_bf16 v[10:13], v[154:157], v[190:193], v[10:13]
	v_mfma_f32_16x16x32_bf16 v[14:17], v[146:149], v[206:209], v[14:17]
	v_mfma_f32_16x16x32_bf16 v[2:5], v[154:157], v[206:209], v[2:5]
	v_mfma_f32_16x16x32_bf16 v[58:61], v[150:153], v[166:169], v[58:61]
	v_mfma_f32_16x16x32_bf16 v[30:33], v[158:161], v[166:169], v[30:33]
	v_mfma_f32_16x16x32_bf16 v[42:45], v[150:153], v[174:177], v[42:45]
	v_mfma_f32_16x16x32_bf16 v[6:9], v[158:161], v[174:177], v[6:9]
	v_mfma_f32_16x16x32_bf16 v[26:29], v[150:153], v[202:205], v[26:29]
	v_mfma_f32_16x16x32_bf16 v[10:13], v[158:161], v[202:205], v[10:13]
	v_mfma_f32_16x16x32_bf16 v[14:17], v[150:153], v[210:213], v[14:17]
	v_mfma_f32_16x16x32_bf16 v[2:5], v[158:161], v[210:213], v[2:5]
	s_setprio 0
	s_barrier
	s_add_i32 s31, s31, 2
	s_add_u32 s29, s29, 0x100
	s_addc_u32 s30, s30, 0
	s_cmp_gt_u32 s31, 29
	s_mov_b64 s[44:45], s[4:5]
	s_cbranch_scc0 .LBB0_1299
	s_and_b64 vcc, exec, s[48:49]
	s_cbranch_vccz .LBB0_1302
	s_barrier

; #define PG8_STAGE(bufoff, gbase, voff) do { _Pragma("unroll") for (int _i = 0; _i < 2; ++_i) \
;         __builtin_amdgcn_global_load_lds((const unsigned*)((const char*)(gbase) + (voff)[_i]), (LAS unsigned*)(lds + (bufoff) + ldsw + _i * 8192), 16, 0, 0); } while (0)
; #define PG8_LDA(dst, b, h) do { _Pragma("unroll") for (int m = 0; m < 4; ++m) _Pragma("unroll") for (int k = 0; k < 2; ++k) dst[m][k] = *(const LAS bf16x8*)(lds + PG8_SA(b, h) + aoff + m * 2048 + k * 1024); } while (0)
; #define PG8_LDB(dst, b, h) do { _Pragma("unroll") for (int n = 0; n < 2; ++n) _Pragma("unroll") for (int k = 0; k < 2; ++k) dst[n][k] = *(const LAS bf16x8*)(lds + PG8_SB(b, h) + boff + n * 2048 + k * 1024); } while (0)
; #define PG8_MMA(ai, bj, At, Bt) do { __builtin_amdgcn_s_setprio(1); _Pragma("unroll") for (int m = 0; m < 4; ++m) _Pragma("unroll") for (int n = 0; n < 2; ++n) _Pragma("unroll") for (int k = 0; k < 2; ++k) \
;         acc[ai][bj][m][n] = __builtin_amdgcn_mfma_f32_16x16x32_bf16(Bt[n][k], At[m][k], acc[ai][bj][m][n], 0, 0, 0); __builtin_amdgcn_s_setprio(0); } while (0)
; #define PG8_WAIT_V(n) asm volatile("s_waitcnt vmcnt(" #n ")" ::: "memory")
; #define PG8_WAIT_L(n) asm volatile("s_waitcnt lgkmcnt(" #n ")" ::: "memory")
; #define PG8_BAR __builtin_amdgcn_s_barrier()
; #define PG8_SCHED __builtin_amdgcn_sched_barrier(0)
; template <class Epi, int AMODE>
; __device__ __forceinline__ void gemm_phase(LAS unsigned char* lds, const Gemm g, const StaticOrder& S, const Epi& E, int stagger_us, int tid_in) {
;     ...
;             PG8_LDB(B0, 0, 0); PG8_LDB(B1, 0, 1); PG8_SCHED; PG8_LDA(At, 0, 0); PG8_STAGE(PG8_SA(1, 1), a1 + hstepA, voffA);
;             PG8_WAIT_V(8); PG8_WAIT_L(0); PG8_BAR; PG8_MMA(0, 0, At, B0); PG8_MMA(0, 1, At, B1); PG8_BAR; PG8_SCHED;
;             PG8_LDA(At, 0, 1); PG8_STAGE(PG8_SB(0, 0), b2, voffB); PG8_STAGE(PG8_SB(0, 1), b2 + hstepB, voffB); PG8_STAGE(PG8_SA(0, 0), a2, voffA);
;             PG8_WAIT_V(8); PG8_WAIT_L(0); PG8_BAR; PG8_MMA(1, 0, At, B0); PG8_MMA(1, 1, At, B1); PG8_BAR; PG8_SCHED;
.LBB0_1476:
	s_add_i32 s30, 0, 0x10000
	s_add_i32 s34, 0, 0x14000
	v_add_u32_e32 v102, s30, v162
	v_add_u32_e32 v165, s34, v162
	ds_read_b128 v[66:69], v102
	ds_read_b128 v[70:73], v102 offset:1024
	ds_read_b128 v[74:77], v102 offset:2048
	ds_read_b128 v[102:105], v102 offset:3072
	ds_read_b128 v[152:155], v165
	ds_read_b128 v[156:159], v165 offset:1024
	ds_read_b128 v[166:169], v165 offset:2048
	ds_read_b128 v[170:173], v165 offset:3072
	ds_read_b128 v[174:177], v164
	ds_read_b128 v[178:181], v164 offset:1024
	ds_read_b128 v[182:185], v164 offset:2048
	ds_read_b128 v[186:189], v164 offset:3072
	ds_read_b128 v[190:193], v164 offset:4096
	ds_read_b128 v[194:197], v164 offset:5120
	ds_read_b128 v[198:201], v164 offset:6144
	ds_read_b128 v[202:205], v164 offset:7168
	s_add_u32 s4, s54, 0x100
	s_addc_u32 s5, s55, 0
	s_cmpk_eq_i32 s29, 0x52
	s_cselect_b32 s57, s41, s5
	s_cselect_b32 s56, s40, s4
	s_cselect_b32 s7, s53, s28
	s_cselect_b32 s6, s52, s27
	s_add_i32 m0, s13, 0xc000
	v_lshl_add_u64 v[206:207], s[54:55], 0, v[148:149]
	global_load_lds_dwordx4 v[206:207], off
	s_add_i32 m0, s13, 0xe000
	v_lshl_add_u64 v[206:207], s[54:55], 0, v[150:151]
	global_load_lds_dwordx4 v[206:207], off
	s_setprio 1
	s_waitcnt vmcnt(8) lgkmcnt(0)
	s_barrier
	v_mfma_f32_16x16x32_bf16 v[142:145], v[66:69], v[174:177], v[142:145]
	v_mfma_f32_16x16x32_bf16 v[138:141], v[74:77], v[174:177], v[138:141]
	v_mfma_f32_16x16x32_bf16 v[134:137], v[66:69], v[182:185], v[134:137]
	v_mfma_f32_16x16x32_bf16 v[130:133], v[74:77], v[182:185], v[130:133]
	v_mfma_f32_16x16x32_bf16 v[110:113], v[66:69], v[190:193], v[110:113]
	v_mfma_f32_16x16x32_bf16 v[106:109], v[74:77], v[190:193], v[106:109]
	v_mfma_f32_16x16x32_bf16 v[98:101], v[66:69], v[198:201], v[98:101]
	v_mfma_f32_16x16x32_bf16 v[94:97], v[74:77], v[198:201], v[94:97]
	v_mfma_f32_16x16x32_bf16 v[142:145], v[70:73], v[178:181], v[142:145]
	v_mfma_f32_16x16x32_bf16 v[138:141], v[102:105], v[178:181], v[138:141]
	v_mfma_f32_16x16x32_bf16 v[134:137], v[70:73], v[186:189], v[134:137]
	v_mfma_f32_16x16x32_bf16 v[130:133], v[102:105], v[186:189], v[130:133]
	v_mfma_f32_16x16x32_bf16 v[110:113], v[70:73], v[194:197], v[110:113]
	v_mfma_f32_16x16x32_bf16 v[106:109], v[102:105], v[194:197], v[106:109]
	v_mfma_f32_16x16x32_bf16 v[98:101], v[70:73], v[202:205], v[98:101]
	v_mfma_f32_16x16x32_bf16 v[94:97], v[102:105], v[202:205], v[94:97]
	v_mfma_f32_16x16x32_bf16 v[126:129], v[152:155], v[174:177], v[126:129]
	v_mfma_f32_16x16x32_bf16 v[122:125], v[166:169], v[174:177], v[122:125]
	v_mfma_f32_16x16x32_bf16 v[118:121], v[152:155], v[182:185], v[118:121]
	v_mfma_f32_16x16x32_bf16 v[114:117], v[166:169], v[182:185], v[114:117]
	v_mfma_f32_16x16x32_bf16 v[90:93], v[152:155], v[190:193], v[90:93]
	v_mfma_f32_16x16x32_bf16 v[86:89], v[166:169], v[190:193], v[86:89]
	v_mfma_f32_16x16x32_bf16 v[82:85], v[152:155], v[198:201], v[82:85]
	v_mfma_f32_16x16x32_bf16 v[78:81], v[166:169], v[198:201], v[78:81]
	v_mfma_f32_16x16x32_bf16 v[126:129], v[156:159], v[178:181], v[126:129]
	v_mfma_f32_16x16x32_bf16 v[122:125], v[170:173], v[178:181], v[122:125]
	v_mfma_f32_16x16x32_bf16 v[118:121], v[156:159], v[186:189], v[118:121]
	v_mfma_f32_16x16x32_bf16 v[114:117], v[170:173], v[186:189], v[114:117]
	v_mfma_f32_16x16x32_bf16 v[90:93], v[156:159], v[194:197], v[90:93]
	v_mfma_f32_16x16x32_bf16 v[86:89], v[170:173], v[194:197], v[86:89]
	v_mfma_f32_16x16x32_bf16 v[82:85], v[156:159], v[202:205], v[82:85]
	v_mfma_f32_16x16x32_bf16 v[78:81], v[170:173], v[202:205], v[78:81]
	s_setprio 0
	s_barrier
	ds_read_b128 v[174:177], v164 offset:16384
	ds_read_b128 v[178:181], v164 offset:17408
	ds_read_b128 v[182:185], v164 offset:18432
	ds_read_b128 v[186:189], v164 offset:19456
	ds_read_b128 v[190:193], v164 offset:20480
	ds_read_b128 v[194:197], v164 offset:21504
	ds_read_b128 v[198:201], v164 offset:22528
	ds_read_b128 v[202:205], v164 offset:23552
	s_add_i32 s30, s30, s12
	s_mov_b32 m0, s30
	v_lshl_add_u64 v[206:207], s[6:7], 0, v[0:1]
	global_load_lds_dwordx4 v[206:207], off
	s_add_i32 m0, s30, 0x2000
	s_add_u32 s30, s6, 0x158000
	v_lshl_add_u64 v[208:209], s[6:7], 0, v[146:147]
	s_addc_u32 s31, s7, 0
	s_add_i32 s34, s34, s12
	global_load_lds_dwordx4 v[208:209], off
	v_lshl_add_u64 v[210:211], s[30:31], 0, v[0:1]
	s_mov_b32 m0, s34
	v_lshl_add_u64 v[212:213], s[56:57], 0, v[146:147]
	global_load_lds_dwordx4 v[210:211], off
	s_add_i32 m0, s34, 0x2000
	v_lshl_add_u64 v[210:211], s[30:31], 0, v[146:147]
	global_load_lds_dwordx4 v[210:211], off
	s_mov_b32 m0, s13
	v_lshl_add_u64 v[210:211], s[56:57], 0, v[0:1]
	global_load_lds_dwordx4 v[210:211], off
	s_mov_b32 m0, s24
	s_nop 0
	global_load_lds_dwordx4 v[212:213], off
	s_setprio 1
	s_waitcnt vmcnt(8) lgkmcnt(0)
	s_barrier
; #define PG8_STAGE(bufoff, gbase, voff) do { _Pragma("unroll") for (int _i = 0; _i < 2; ++_i) \
;         __builtin_amdgcn_global_load_lds((const unsigned*)((const char*)(gbase) + (voff)[_i]), (LAS unsigned*)(lds + (bufoff) + ldsw + _i * 8192), 16, 0, 0); } while (0)
; #define PG8_LDA(dst, b, h) do { _Pragma("unroll") for (int m = 0; m < 4; ++m) _Pragma("unroll") for (int k = 0; k < 2; ++k) dst[m][k] = *(const LAS bf16x8*)(lds + PG8_SA(b, h) + aoff + m * 2048 + k * 1024); } while (0)
; #define PG8_LDB(dst, b, h) do { _Pragma("unroll") for (int n = 0; n < 2; ++n) _Pragma("unroll") for (int k = 0; k < 2; ++k) dst[n][k] = *(const LAS bf16x8*)(lds + PG8_SB(b, h) + boff + n * 2048 + k * 1024); } while (0)
; #define PG8_MMA(ai, bj, At, Bt) do { __builtin_amdgcn_s_setprio(1); _Pragma("unroll") for (int m = 0; m < 4; ++m) _Pragma("unroll") for (int n = 0; n < 2; ++n) _Pragma("unroll") for (int k = 0; k < 2; ++k) \
;         acc[ai][bj][m][n] = __builtin_amdgcn_mfma_f32_16x16x32_bf16(Bt[n][k], At[m][k], acc[ai][bj][m][n], 0, 0, 0); __builtin_amdgcn_s_setprio(0); } while (0)
; #define PG8_WAIT_V(n) asm volatile("s_waitcnt vmcnt(" #n ")" ::: "memory")
; #define PG8_WAIT_L(n) asm volatile("s_waitcnt lgkmcnt(" #n ")" ::: "memory")
; #define PG8_BAR __builtin_amdgcn_s_barrier()
; #define PG8_SCHED __builtin_amdgcn_sched_barrier(0)
; template <class Epi, int AMODE>
; __device__ __forceinline__ void gemm_phase(LAS unsigned char* lds, const Gemm g, const StaticOrder& S, const Epi& E, int stagger_us, int tid_in) {
;     ...
;             PG8_WAIT_V(8); PG8_WAIT_L(0); PG8_BAR; PG8_MMA(1, 0, At, B0); PG8_MMA(1, 1, At, B1); PG8_BAR; PG8_SCHED;
;             PG8_LDB(B0, 1, 0); PG8_LDB(B1, 1, 1); PG8_SCHED; PG8_LDA(At, 1, 0); PG8_STAGE(PG8_SA(0, 1), a2 + hstepA, voffA);
;             PG8_WAIT_V(8); PG8_WAIT_L(0); PG8_BAR; PG8_MMA(0, 0, At, B0); PG8_MMA(0, 1, At, B1); PG8_BAR; PG8_SCHED;
	v_mfma_f32_16x16x32_bf16 v[62:65], v[66:69], v[174:177], v[62:65]
	v_mfma_f32_16x16x32_bf16 v[58:61], v[74:77], v[174:177], v[58:61]
	v_mfma_f32_16x16x32_bf16 v[54:57], v[66:69], v[182:185], v[54:57]
	v_mfma_f32_16x16x32_bf16 v[50:53], v[74:77], v[182:185], v[50:53]
	v_mfma_f32_16x16x32_bf16 v[30:33], v[66:69], v[190:193], v[30:33]
	v_mfma_f32_16x16x32_bf16 v[26:29], v[74:77], v[190:193], v[26:29]
	v_mfma_f32_16x16x32_bf16 v[22:25], v[66:69], v[198:201], v[22:25]
	v_mfma_f32_16x16x32_bf16 v[10:13], v[74:77], v[198:201], v[10:13]
	v_mfma_f32_16x16x32_bf16 v[62:65], v[70:73], v[178:181], v[62:65]
	v_mfma_f32_16x16x32_bf16 v[58:61], v[102:105], v[178:181], v[58:61]
	v_mfma_f32_16x16x32_bf16 v[54:57], v[70:73], v[186:189], v[54:57]
	v_mfma_f32_16x16x32_bf16 v[50:53], v[102:105], v[186:189], v[50:53]
	v_mfma_f32_16x16x32_bf16 v[30:33], v[70:73], v[194:197], v[30:33]
	v_mfma_f32_16x16x32_bf16 v[26:29], v[102:105], v[194:197], v[26:29]
	v_mfma_f32_16x16x32_bf16 v[22:25], v[70:73], v[202:205], v[22:25]
	v_mfma_f32_16x16x32_bf16 v[10:13], v[102:105], v[202:205], v[10:13]
	v_mfma_f32_16x16x32_bf16 v[46:49], v[152:155], v[174:177], v[46:49]
	v_mfma_f32_16x16x32_bf16 v[42:45], v[166:169], v[174:177], v[42:45]
	v_mfma_f32_16x16x32_bf16 v[38:41], v[152:155], v[182:185], v[38:41]
	v_mfma_f32_16x16x32_bf16 v[34:37], v[166:169], v[182:185], v[34:37]
	v_mfma_f32_16x16x32_bf16 v[18:21], v[152:155], v[190:193], v[18:21]
	v_mfma_f32_16x16x32_bf16 v[14:17], v[166:169], v[190:193], v[14:17]
	v_mfma_f32_16x16x32_bf16 v[6:9], v[152:155], v[198:201], v[6:9]
	v_mfma_f32_16x16x32_bf16 v[2:5], v[166:169], v[198:201], v[2:5]
	v_mfma_f32_16x16x32_bf16 v[46:49], v[156:159], v[178:181], v[46:49]
	v_mfma_f32_16x16x32_bf16 v[42:45], v[170:173], v[178:181], v[42:45]
	v_mfma_f32_16x16x32_bf16 v[38:41], v[156:159], v[186:189], v[38:41]
	v_mfma_f32_16x16x32_bf16 v[34:37], v[170:173], v[186:189], v[34:37]
	v_mfma_f32_16x16x32_bf16 v[18:21], v[156:159], v[194:197], v[18:21]
	v_mfma_f32_16x16x32_bf16 v[14:17], v[170:173], v[194:197], v[14:17]
	v_mfma_f32_16x16x32_bf16 v[6:9], v[156:159], v[202:205], v[6:9]
	v_mfma_f32_16x16x32_bf16 v[2:5], v[170:173], v[202:205], v[2:5]
	s_setprio 0
	s_barrier
	s_add_i32 s34, 0, 0x18000
	s_add_i32 s35, 0, 0x1c000
	v_add_u32_e32 v102, s34, v162
	v_add_u32_e32 v165, s35, v162
	ds_read_b128 v[66:69], v102
	ds_read_b128 v[70:73], v102 offset:1024
	ds_read_b128 v[74:77], v102 offset:2048
	ds_read_b128 v[102:105], v102 offset:3072
	ds_read_b128 v[152:155], v165
	ds_read_b128 v[156:159], v165 offset:1024
	ds_read_b128 v[166:169], v165 offset:2048
	ds_read_b128 v[170:173], v165 offset:3072
	ds_read_b128 v[174:177], v164 offset:32768
	ds_read_b128 v[178:181], v164 offset:33792
	ds_read_b128 v[182:185], v164 offset:34816
	ds_read_b128 v[186:189], v164 offset:35840
	ds_read_b128 v[190:193], v164 offset:36864
	ds_read_b128 v[194:197], v164 offset:37888
	ds_read_b128 v[198:201], v164 offset:38912
	ds_read_b128 v[202:205], v164 offset:39936
	s_add_u32 s30, s56, 0x158000
	s_addc_u32 s31, s57, 0
	s_mov_b32 m0, s25
	v_lshl_add_u64 v[214:215], s[30:31], 0, v[0:1]
	global_load_lds_dwordx4 v[214:215], off
	s_mov_b32 m0, s66
	v_lshl_add_u64 v[214:215], s[30:31], 0, v[146:147]
	global_load_lds_dwordx4 v[214:215], off
	s_setprio 1
	s_waitcnt vmcnt(8) lgkmcnt(0)
	s_barrier
	v_mfma_f32_16x16x32_bf16 v[142:145], v[66:69], v[174:177], v[142:145]
	v_mfma_f32_16x16x32_bf16 v[138:141], v[74:77], v[174:177], v[138:141]
	v_mfma_f32_16x16x32_bf16 v[134:137], v[66:69], v[182:185], v[134:137]
	v_mfma_f32_16x16x32_bf16 v[130:133], v[74:77], v[182:185], v[130:133]
	v_mfma_f32_16x16x32_bf16 v[110:113], v[66:69], v[190:193], v[110:113]
	v_mfma_f32_16x16x32_bf16 v[106:109], v[74:77], v[190:193], v[106:109]
	v_mfma_f32_16x16x32_bf16 v[98:101], v[66:69], v[198:201], v[98:101]
	v_mfma_f32_16x16x32_bf16 v[94:97], v[74:77], v[198:201], v[94:97]
	v_mfma_f32_16x16x32_bf16 v[142:145], v[70:73], v[178:181], v[142:145]
	v_mfma_f32_16x16x32_bf16 v[138:141], v[102:105], v[178:181], v[138:141]
	v_mfma_f32_16x16x32_bf16 v[134:137], v[70:73], v[186:189], v[134:137]
	v_mfma_f32_16x16x32_bf16 v[130:133], v[102:105], v[186:189], v[130:133]
	v_mfma_f32_16x16x32_bf16 v[110:113], v[70:73], v[194:197], v[110:113]
	v_mfma_f32_16x16x32_bf16 v[106:109], v[102:105], v[194:197], v[106:109]
	v_mfma_f32_16x16x32_bf16 v[98:101], v[70:73], v[202:205], v[98:101]
	v_mfma_f32_16x16x32_bf16 v[94:97], v[102:105], v[202:205], v[94:97]
	v_mfma_f32_16x16x32_bf16 v[126:129], v[152:155], v[174:177], v[126:129]
	v_mfma_f32_16x16x32_bf16 v[122:125], v[166:169], v[174:177], v[122:125]
	v_mfma_f32_16x16x32_bf16 v[118:121], v[152:155], v[182:185], v[118:121]
	v_mfma_f32_16x16x32_bf16 v[114:117], v[166:169], v[182:185], v[114:117]
	v_mfma_f32_16x16x32_bf16 v[90:93], v[152:155], v[190:193], v[90:93]
	v_mfma_f32_16x16x32_bf16 v[86:89], v[166:169], v[190:193], v[86:89]
	v_mfma_f32_16x16x32_bf16 v[82:85], v[152:155], v[198:201], v[82:85]
	v_mfma_f32_16x16x32_bf16 v[78:81], v[166:169], v[198:201], v[78:81]
	v_mfma_f32_16x16x32_bf16 v[126:129], v[156:159], v[178:181], v[126:129]
	v_mfma_f32_16x16x32_bf16 v[122:125], v[170:173], v[178:181], v[122:125]
	v_mfma_f32_16x16x32_bf16 v[118:121], v[156:159], v[186:189], v[118:121]
	v_mfma_f32_16x16x32_bf16 v[114:117], v[170:173], v[186:189], v[114:117]
	v_mfma_f32_16x16x32_bf16 v[90:93], v[156:159], v[194:197], v[90:93]
	v_mfma_f32_16x16x32_bf16 v[86:89], v[170:173], v[194:197], v[86:89]
	v_mfma_f32_16x16x32_bf16 v[82:85], v[156:159], v[202:205], v[82:85]
	v_mfma_f32_16x16x32_bf16 v[78:81], v[170:173], v[202:205], v[78:81]
	s_setprio 0
	s_barrier
; #define PG8_STAGE(bufoff, gbase, voff) do { _Pragma("unroll") for (int _i = 0; _i < 2; ++_i) \
;         __builtin_amdgcn_global_load_lds((const unsigned*)((const char*)(gbase) + (voff)[_i]), (LAS unsigned*)(lds + (bufoff) + ldsw + _i * 8192), 16, 0, 0); } while (0)
; #define PG8_LDA(dst, b, h) do { _Pragma("unroll") for (int m = 0; m < 4; ++m) _Pragma("unroll") for (int k = 0; k < 2; ++k) dst[m][k] = *(const LAS bf16x8*)(lds + PG8_SA(b, h) + aoff + m * 2048 + k * 1024); } while (0)
; #define PG8_MMA(ai, bj, At, Bt) do { __builtin_amdgcn_s_setprio(1); _Pragma("unroll") for (int m = 0; m < 4; ++m) _Pragma("unroll") for (int n = 0; n < 2; ++n) _Pragma("unroll") for (int k = 0; k < 2; ++k) \
;         acc[ai][bj][m][n] = __builtin_amdgcn_mfma_f32_16x16x32_bf16(Bt[n][k], At[m][k], acc[ai][bj][m][n], 0, 0, 0); __builtin_amdgcn_s_setprio(0); } while (0)
; #define PG8_WAIT_V(n) asm volatile("s_waitcnt vmcnt(" #n ")" ::: "memory")
; #define PG8_WAIT_L(n) asm volatile("s_waitcnt lgkmcnt(" #n ")" ::: "memory")
; #define PG8_BAR __builtin_amdgcn_s_barrier()
; #define PG8_SCHED __builtin_amdgcn_sched_barrier(0)
; template <class Epi, int AMODE>
; __device__ __forceinline__ void gemm_phase(LAS unsigned char* lds, const Gemm g, const StaticOrder& S, const Epi& E, int stagger_us, int tid_in) {
;     ...
;             PG8_LDA(At, 1, 1); PG8_STAGE(PG8_SB(1, 0), b3, voffB); PG8_STAGE(PG8_SB(1, 1), b3 + hstepB, voffB); PG8_STAGE(PG8_SA(1, 0), a3, voffA);
;             PG8_WAIT_V(8); PG8_WAIT_L(0); PG8_BAR; PG8_MMA(1, 0, At, B0); PG8_MMA(1, 1, At, B1); PG8_BAR; PG8_SCHED;
;         }
;         if (wr == 0) PG8_BAR;
	ds_read_b128 v[174:177], v164 offset:49152
	ds_read_b128 v[178:181], v164 offset:50176
	ds_read_b128 v[182:185], v164 offset:51200
	ds_read_b128 v[186:189], v164 offset:52224
	ds_read_b128 v[190:193], v164 offset:53248
	ds_read_b128 v[194:197], v164 offset:54272
	ds_read_b128 v[198:201], v164 offset:55296
	ds_read_b128 v[202:205], v164 offset:56320
	s_add_i32 s30, s34, s12
	s_mov_b32 m0, s30
	v_lshl_add_u64 v[206:207], v[206:207], 0, s[74:75]
	global_load_lds_dwordx4 v[206:207], off
	s_add_i32 m0, s30, 0x2000
	s_add_u32 s6, s6, 0x158080
	v_lshl_add_u64 v[206:207], v[208:209], 0, s[74:75]
	s_addc_u32 s7, s7, 0
	s_add_i32 s30, s35, s12
	global_load_lds_dwordx4 v[206:207], off
	s_mov_b32 m0, s30
	v_lshl_add_u64 v[206:207], s[6:7], 0, v[0:1]
	global_load_lds_dwordx4 v[206:207], off
	s_add_i32 m0, s30, 0x2000
	v_lshl_add_u64 v[206:207], s[6:7], 0, v[146:147]
	global_load_lds_dwordx4 v[206:207], off
	s_mov_b32 m0, s67
	v_lshl_add_u64 v[206:207], v[210:211], 0, s[74:75]
	global_load_lds_dwordx4 v[206:207], off
	s_mov_b32 m0, s69
	v_lshl_add_u64 v[206:207], v[212:213], 0, s[74:75]
	global_load_lds_dwordx4 v[206:207], off
	s_setprio 1
	s_waitcnt vmcnt(8) lgkmcnt(0)
	s_barrier
	v_mfma_f32_16x16x32_bf16 v[62:65], v[66:69], v[174:177], v[62:65]
	v_mfma_f32_16x16x32_bf16 v[58:61], v[74:77], v[174:177], v[58:61]
	v_mfma_f32_16x16x32_bf16 v[54:57], v[66:69], v[182:185], v[54:57]
	v_mfma_f32_16x16x32_bf16 v[50:53], v[74:77], v[182:185], v[50:53]
	v_mfma_f32_16x16x32_bf16 v[30:33], v[66:69], v[190:193], v[30:33]
	v_mfma_f32_16x16x32_bf16 v[26:29], v[74:77], v[190:193], v[26:29]
	v_mfma_f32_16x16x32_bf16 v[22:25], v[66:69], v[198:201], v[22:25]
	v_mfma_f32_16x16x32_bf16 v[10:13], v[74:77], v[198:201], v[10:13]
	v_mfma_f32_16x16x32_bf16 v[62:65], v[70:73], v[178:181], v[62:65]
	v_mfma_f32_16x16x32_bf16 v[58:61], v[102:105], v[178:181], v[58:61]
	v_mfma_f32_16x16x32_bf16 v[54:57], v[70:73], v[186:189], v[54:57]
	v_mfma_f32_16x16x32_bf16 v[50:53], v[102:105], v[186:189], v[50:53]
	v_mfma_f32_16x16x32_bf16 v[30:33], v[70:73], v[194:197], v[30:33]
	v_mfma_f32_16x16x32_bf16 v[26:29], v[102:105], v[194:197], v[26:29]
	v_mfma_f32_16x16x32_bf16 v[22:25], v[70:73], v[202:205], v[22:25]
	v_mfma_f32_16x16x32_bf16 v[10:13], v[102:105], v[202:205], v[10:13]
	v_mfma_f32_16x16x32_bf16 v[46:49], v[152:155], v[174:177], v[46:49]
	v_mfma_f32_16x16x32_bf16 v[42:45], v[166:169], v[174:177], v[42:45]
	v_mfma_f32_16x16x32_bf16 v[38:41], v[152:155], v[182:185], v[38:41]
	v_mfma_f32_16x16x32_bf16 v[34:37], v[166:169], v[182:185], v[34:37]
	v_mfma_f32_16x16x32_bf16 v[18:21], v[152:155], v[190:193], v[18:21]
	v_mfma_f32_16x16x32_bf16 v[14:17], v[166:169], v[190:193], v[14:17]
	v_mfma_f32_16x16x32_bf16 v[6:9], v[152:155], v[198:201], v[6:9]
	v_mfma_f32_16x16x32_bf16 v[2:5], v[166:169], v[198:201], v[2:5]
	v_mfma_f32_16x16x32_bf16 v[46:49], v[156:159], v[178:181], v[46:49]
	v_mfma_f32_16x16x32_bf16 v[42:45], v[170:173], v[178:181], v[42:45]
	v_mfma_f32_16x16x32_bf16 v[38:41], v[156:159], v[186:189], v[38:41]
	v_mfma_f32_16x16x32_bf16 v[34:37], v[170:173], v[186:189], v[34:37]
	v_mfma_f32_16x16x32_bf16 v[18:21], v[156:159], v[194:197], v[18:21]
	v_mfma_f32_16x16x32_bf16 v[14:17], v[170:173], v[194:197], v[14:17]
	v_mfma_f32_16x16x32_bf16 v[6:9], v[156:159], v[202:205], v[6:9]
	v_mfma_f32_16x16x32_bf16 v[2:5], v[170:173], v[202:205], v[2:5]
	s_setprio 0
	s_barrier
	s_add_i32 s29, s29, 2
	s_add_u32 s27, s27, 0x100
	s_addc_u32 s28, s28, 0
	s_cmpk_gt_u32 s29, 0x53
	s_mov_b64 s[54:55], s[4:5]
	s_cbranch_scc0 .LBB0_1476
	s_and_b64 vcc, exec, s[46:47]
	s_cbranch_vccz .LBB0_1479
	s_barrier

; #define PG8_STAGE(bufoff, gbase, voff) do { _Pragma("unroll") for (int _i = 0; _i < 2; ++_i) \
;         __builtin_amdgcn_global_load_lds((const unsigned*)((const char*)(gbase) + (voff)[_i]), (LAS unsigned*)(lds + (bufoff) + ldsw + _i * 8192), 16, 0, 0); } while (0)
; #define PG8_LDA(dst, b, h) do { _Pragma("unroll") for (int m = 0; m < 4; ++m) _Pragma("unroll") for (int k = 0; k < 2; ++k) dst[m][k] = *(const LAS bf16x8*)(lds + PG8_SA(b, h) + aoff + m * 2048 + k * 1024); } while (0)
; #define PG8_LDB(dst, b, h) do { _Pragma("unroll") for (int n = 0; n < 2; ++n) _Pragma("unroll") for (int k = 0; k < 2; ++k) dst[n][k] = *(const LAS bf16x8*)(lds + PG8_SB(b, h) + boff + n * 2048 + k * 1024); } while (0)
; #define PG8_MMA(ai, bj, At, Bt) do { __builtin_amdgcn_s_setprio(1); _Pragma("unroll") for (int m = 0; m < 4; ++m) _Pragma("unroll") for (int n = 0; n < 2; ++n) _Pragma("unroll") for (int k = 0; k < 2; ++k) \
;         acc[ai][bj][m][n] = __builtin_amdgcn_mfma_f32_16x16x32_bf16(Bt[n][k], At[m][k], acc[ai][bj][m][n], 0, 0, 0); __builtin_amdgcn_s_setprio(0); } while (0)
; #define PG8_WAIT_V(n) asm volatile("s_waitcnt vmcnt(" #n ")" ::: "memory")
; #define PG8_WAIT_L(n) asm volatile("s_waitcnt lgkmcnt(" #n ")" ::: "memory")
; #define PG8_BAR __builtin_amdgcn_s_barrier()
; #define PG8_SCHED __builtin_amdgcn_sched_barrier(0)
; template <class Epi, int AMODE>
; __device__ __forceinline__ void gemm_phase(LAS unsigned char* lds, const Gemm g, const StaticOrder& S, const Epi& E, int stagger_us, int tid_in) {
;     ...
;             PG8_LDB(B0, 0, 0); PG8_LDB(B1, 0, 1); PG8_SCHED; PG8_LDA(At, 0, 0); PG8_STAGE(PG8_SA(1, 1), a1 + hstepA, voffA);
;             PG8_WAIT_V(8); PG8_WAIT_L(0); PG8_BAR; PG8_MMA(0, 0, At, B0); PG8_MMA(0, 1, At, B1); PG8_BAR; PG8_SCHED;
;             PG8_LDA(At, 0, 1); PG8_STAGE(PG8_SB(0, 0), b2, voffB); PG8_STAGE(PG8_SB(0, 1), b2 + hstepB, voffB); PG8_STAGE(PG8_SA(0, 0), a2, voffA);
;             PG8_WAIT_V(8); PG8_WAIT_L(0); PG8_BAR; PG8_MMA(1, 0, At, B0); PG8_MMA(1, 1, At, B1); PG8_BAR; PG8_SCHED;
.LBB0_1498:
	s_add_i32 s30, 0, 0x10000
	s_add_i32 s34, 0, 0x14000
	v_add_u32_e32 v62, s30, v209
	v_add_u32_e32 v158, s34, v209
	ds_read_b128 v[50:53], v62
	ds_read_b128 v[54:57], v62 offset:1024
	ds_read_b128 v[58:61], v62 offset:2048
	ds_read_b128 v[62:65], v62 offset:3072
	ds_read_b128 v[146:149], v158
	ds_read_b128 v[150:153], v158 offset:1024
	ds_read_b128 v[154:157], v158 offset:2048
	ds_read_b128 v[158:161], v158 offset:3072
	ds_read_b128 v[162:165], v215
	ds_read_b128 v[166:169], v215 offset:1024
	ds_read_b128 v[170:173], v215 offset:2048
	ds_read_b128 v[180:183], v215 offset:3072
	ds_read_b128 v[184:187], v215 offset:4096
	ds_read_b128 v[188:191], v215 offset:5120
	ds_read_b128 v[192:195], v215 offset:6144
	ds_read_b128 v[196:199], v215 offset:7168
	s_add_u32 s4, s46, 0x100
	s_addc_u32 s5, s47, 0
	s_cmpk_eq_i32 s29, 0x52
	s_cselect_b32 s59, s41, s5
	s_cselect_b32 s58, s40, s4
	s_cselect_b32 s7, s57, s28
	s_cselect_b32 s6, s56, s27
	s_add_i32 m0, s13, 0xc000
	v_lshl_add_u64 v[200:201], s[46:47], 0, v[176:177]
	global_load_lds_dwordx4 v[200:201], off
	s_add_i32 m0, s13, 0xe000
	v_lshl_add_u64 v[200:201], s[46:47], 0, v[178:179]
	global_load_lds_dwordx4 v[200:201], off
	s_setprio 1
	s_waitcnt vmcnt(8) lgkmcnt(0)
	s_barrier
	v_mfma_f32_16x16x32_bf16 v[142:145], v[50:53], v[162:165], v[142:145]
	v_mfma_f32_16x16x32_bf16 v[138:141], v[58:61], v[162:165], v[138:141]
	v_mfma_f32_16x16x32_bf16 v[126:129], v[50:53], v[170:173], v[126:129]
	v_mfma_f32_16x16x32_bf16 v[122:125], v[58:61], v[170:173], v[122:125]
	v_mfma_f32_16x16x32_bf16 v[110:113], v[50:53], v[184:187], v[110:113]
	v_mfma_f32_16x16x32_bf16 v[106:109], v[58:61], v[184:187], v[106:109]
	v_mfma_f32_16x16x32_bf16 v[94:97], v[50:53], v[192:195], v[94:97]
	v_mfma_f32_16x16x32_bf16 v[90:93], v[58:61], v[192:195], v[90:93]
	v_mfma_f32_16x16x32_bf16 v[142:145], v[54:57], v[166:169], v[142:145]
	v_mfma_f32_16x16x32_bf16 v[138:141], v[62:65], v[166:169], v[138:141]
	v_mfma_f32_16x16x32_bf16 v[126:129], v[54:57], v[180:183], v[126:129]
	v_mfma_f32_16x16x32_bf16 v[122:125], v[62:65], v[180:183], v[122:125]
	v_mfma_f32_16x16x32_bf16 v[110:113], v[54:57], v[188:191], v[110:113]
	v_mfma_f32_16x16x32_bf16 v[106:109], v[62:65], v[188:191], v[106:109]
	v_mfma_f32_16x16x32_bf16 v[94:97], v[54:57], v[196:199], v[94:97]
	v_mfma_f32_16x16x32_bf16 v[90:93], v[62:65], v[196:199], v[90:93]
	v_mfma_f32_16x16x32_bf16 v[134:137], v[146:149], v[162:165], v[134:137]
	v_mfma_f32_16x16x32_bf16 v[130:133], v[154:157], v[162:165], v[130:133]
	v_mfma_f32_16x16x32_bf16 v[118:121], v[146:149], v[170:173], v[118:121]
	v_mfma_f32_16x16x32_bf16 v[114:117], v[154:157], v[170:173], v[114:117]
	v_mfma_f32_16x16x32_bf16 v[102:105], v[146:149], v[184:187], v[102:105]
	v_mfma_f32_16x16x32_bf16 v[98:101], v[154:157], v[184:187], v[98:101]
	v_mfma_f32_16x16x32_bf16 v[86:89], v[146:149], v[192:195], v[86:89]
	v_mfma_f32_16x16x32_bf16 v[82:85], v[154:157], v[192:195], v[82:85]
	v_mfma_f32_16x16x32_bf16 v[134:137], v[150:153], v[166:169], v[134:137]
	v_mfma_f32_16x16x32_bf16 v[130:133], v[158:161], v[166:169], v[130:133]
	v_mfma_f32_16x16x32_bf16 v[118:121], v[150:153], v[180:183], v[118:121]
	v_mfma_f32_16x16x32_bf16 v[114:117], v[158:161], v[180:183], v[114:117]
	v_mfma_f32_16x16x32_bf16 v[102:105], v[150:153], v[188:191], v[102:105]
	v_mfma_f32_16x16x32_bf16 v[98:101], v[158:161], v[188:191], v[98:101]
	v_mfma_f32_16x16x32_bf16 v[86:89], v[150:153], v[196:199], v[86:89]
	v_mfma_f32_16x16x32_bf16 v[82:85], v[158:161], v[196:199], v[82:85]
	s_setprio 0
	s_barrier
	ds_read_b128 v[162:165], v215 offset:16384
	ds_read_b128 v[166:169], v215 offset:17408
	ds_read_b128 v[170:173], v215 offset:18432
	ds_read_b128 v[180:183], v215 offset:19456
	ds_read_b128 v[184:187], v215 offset:20480
	ds_read_b128 v[188:191], v215 offset:21504
	ds_read_b128 v[192:195], v215 offset:22528
	ds_read_b128 v[196:199], v215 offset:23552
	s_add_i32 s30, s30, s12
	s_mov_b32 m0, s30
	v_lshl_add_u64 v[200:201], s[6:7], 0, v[0:1]
	global_load_lds_dwordx4 v[200:201], off
	s_add_i32 m0, s30, 0x2000
	s_add_u32 s30, s6, 0x158000
	v_lshl_add_u64 v[202:203], s[6:7], 0, v[174:175]
	s_addc_u32 s31, s7, 0
	s_add_i32 s34, s34, s12
	global_load_lds_dwordx4 v[202:203], off
	v_lshl_add_u64 v[204:205], s[30:31], 0, v[0:1]
	s_mov_b32 m0, s34
	v_lshl_add_u64 v[206:207], s[58:59], 0, v[174:175]
	global_load_lds_dwordx4 v[204:205], off
	s_add_i32 m0, s34, 0x2000
	v_lshl_add_u64 v[204:205], s[30:31], 0, v[174:175]
	global_load_lds_dwordx4 v[204:205], off
	s_mov_b32 m0, s13
	v_lshl_add_u64 v[204:205], s[58:59], 0, v[0:1]
	global_load_lds_dwordx4 v[204:205], off
	s_mov_b32 m0, s24
	s_nop 0
	global_load_lds_dwordx4 v[206:207], off
	s_setprio 1
	s_waitcnt vmcnt(8) lgkmcnt(0)
	s_barrier
; #define PG8_STAGE(bufoff, gbase, voff) do { _Pragma("unroll") for (int _i = 0; _i < 2; ++_i) \
;         __builtin_amdgcn_global_load_lds((const unsigned*)((const char*)(gbase) + (voff)[_i]), (LAS unsigned*)(lds + (bufoff) + ldsw + _i * 8192), 16, 0, 0); } while (0)
; #define PG8_LDA(dst, b, h) do { _Pragma("unroll") for (int m = 0; m < 4; ++m) _Pragma("unroll") for (int k = 0; k < 2; ++k) dst[m][k] = *(const LAS bf16x8*)(lds + PG8_SA(b, h) + aoff + m * 2048 + k * 1024); } while (0)
; #define PG8_LDB(dst, b, h) do { _Pragma("unroll") for (int n = 0; n < 2; ++n) _Pragma("unroll") for (int k = 0; k < 2; ++k) dst[n][k] = *(const LAS bf16x8*)(lds + PG8_SB(b, h) + boff + n * 2048 + k * 1024); } while (0)
; #define PG8_MMA(ai, bj, At, Bt) do { __builtin_amdgcn_s_setprio(1); _Pragma("unroll") for (int m = 0; m < 4; ++m) _Pragma("unroll") for (int n = 0; n < 2; ++n) _Pragma("unroll") for (int k = 0; k < 2; ++k) \
;         acc[ai][bj][m][n] = __builtin_amdgcn_mfma_f32_16x16x32_bf16(Bt[n][k], At[m][k], acc[ai][bj][m][n], 0, 0, 0); __builtin_amdgcn_s_setprio(0); } while (0)
; #define PG8_WAIT_V(n) asm volatile("s_waitcnt vmcnt(" #n ")" ::: "memory")
; #define PG8_WAIT_L(n) asm volatile("s_waitcnt lgkmcnt(" #n ")" ::: "memory")
; #define PG8_BAR __builtin_amdgcn_s_barrier()
; #define PG8_SCHED __builtin_amdgcn_sched_barrier(0)
; template <class Epi, int AMODE>
; __device__ __forceinline__ void gemm_phase(LAS unsigned char* lds, const Gemm g, const StaticOrder& S, const Epi& E, int stagger_us, int tid_in) {
;     ...
;             PG8_WAIT_V(8); PG8_WAIT_L(0); PG8_BAR; PG8_MMA(1, 0, At, B0); PG8_MMA(1, 1, At, B1); PG8_BAR; PG8_SCHED;
;             PG8_LDB(B0, 1, 0); PG8_LDB(B1, 1, 1); PG8_SCHED; PG8_LDA(At, 1, 0); PG8_STAGE(PG8_SA(0, 1), a2 + hstepA, voffA);
;             PG8_WAIT_V(8); PG8_WAIT_L(0); PG8_BAR; PG8_MMA(0, 0, At, B0); PG8_MMA(0, 1, At, B1); PG8_BAR; PG8_SCHED;
	v_mfma_f32_16x16x32_bf16 v[78:81], v[50:53], v[162:165], v[78:81]
	v_mfma_f32_16x16x32_bf16 v[74:77], v[58:61], v[162:165], v[74:77]
	v_mfma_f32_16x16x32_bf16 v[46:49], v[50:53], v[170:173], v[46:49]
	v_mfma_f32_16x16x32_bf16 v[42:45], v[58:61], v[170:173], v[42:45]
	v_mfma_f32_16x16x32_bf16 v[30:33], v[50:53], v[184:187], v[30:33]
	v_mfma_f32_16x16x32_bf16 v[26:29], v[58:61], v[184:187], v[26:29]
	v_mfma_f32_16x16x32_bf16 v[14:17], v[50:53], v[192:195], v[14:17]
	v_mfma_f32_16x16x32_bf16 v[10:13], v[58:61], v[192:195], v[10:13]
	v_mfma_f32_16x16x32_bf16 v[78:81], v[54:57], v[166:169], v[78:81]
	v_mfma_f32_16x16x32_bf16 v[74:77], v[62:65], v[166:169], v[74:77]
	v_mfma_f32_16x16x32_bf16 v[46:49], v[54:57], v[180:183], v[46:49]
	v_mfma_f32_16x16x32_bf16 v[42:45], v[62:65], v[180:183], v[42:45]
	v_mfma_f32_16x16x32_bf16 v[30:33], v[54:57], v[188:191], v[30:33]
	v_mfma_f32_16x16x32_bf16 v[26:29], v[62:65], v[188:191], v[26:29]
	v_mfma_f32_16x16x32_bf16 v[14:17], v[54:57], v[196:199], v[14:17]
	v_mfma_f32_16x16x32_bf16 v[10:13], v[62:65], v[196:199], v[10:13]
	v_mfma_f32_16x16x32_bf16 v[38:41], v[146:149], v[170:173], v[38:41]
	v_mfma_f32_16x16x32_bf16 v[34:37], v[154:157], v[170:173], v[34:37]
	v_mfma_f32_16x16x32_bf16 v[22:25], v[146:149], v[184:187], v[22:25]
	v_mfma_f32_16x16x32_bf16 v[18:21], v[154:157], v[184:187], v[18:21]
	v_mfma_f32_16x16x32_bf16 v[6:9], v[146:149], v[192:195], v[6:9]
	v_mfma_f32_16x16x32_bf16 v[2:5], v[154:157], v[192:195], v[2:5]
	v_mfma_f32_16x16x32_bf16 v[50:53], v[146:149], v[162:165], v[70:73]
	v_mfma_f32_16x16x32_bf16 v[54:57], v[154:157], v[162:165], v[66:69]
	v_mfma_f32_16x16x32_bf16 v[38:41], v[150:153], v[180:183], v[38:41]
	v_mfma_f32_16x16x32_bf16 v[34:37], v[158:161], v[180:183], v[34:37]
	v_mfma_f32_16x16x32_bf16 v[22:25], v[150:153], v[188:191], v[22:25]
	v_mfma_f32_16x16x32_bf16 v[18:21], v[158:161], v[188:191], v[18:21]
	v_mfma_f32_16x16x32_bf16 v[6:9], v[150:153], v[196:199], v[6:9]
	v_mfma_f32_16x16x32_bf16 v[2:5], v[158:161], v[196:199], v[2:5]
	v_mfma_f32_16x16x32_bf16 v[50:53], v[150:153], v[166:169], v[50:53]
	v_mfma_f32_16x16x32_bf16 v[54:57], v[158:161], v[166:169], v[54:57]
	s_setprio 0
	s_barrier
	s_add_i32 s34, 0, 0x18000
	s_add_i32 s35, 0, 0x1c000
	v_add_u32_e32 v70, s34, v209
	v_add_u32_e32 v158, s35, v209
	ds_read_b128 v[58:61], v70
	ds_read_b128 v[62:65], v70 offset:1024
	ds_read_b128 v[66:69], v70 offset:2048
	ds_read_b128 v[70:73], v70 offset:3072
	ds_read_b128 v[146:149], v158
	ds_read_b128 v[150:153], v158 offset:1024
	ds_read_b128 v[154:157], v158 offset:2048
	ds_read_b128 v[158:161], v158 offset:3072
	ds_read_b128 v[162:165], v215 offset:32768
	ds_read_b128 v[166:169], v215 offset:33792
	ds_read_b128 v[170:173], v215 offset:34816
	ds_read_b128 v[180:183], v215 offset:35840
	ds_read_b128 v[184:187], v215 offset:36864
	ds_read_b128 v[188:191], v215 offset:37888
	ds_read_b128 v[192:195], v215 offset:38912
	ds_read_b128 v[196:199], v215 offset:39936
	s_add_u32 s30, s58, 0x158000
	s_addc_u32 s31, s59, 0
	s_mov_b32 m0, s25
	v_lshl_add_u64 v[210:211], s[30:31], 0, v[0:1]
	global_load_lds_dwordx4 v[210:211], off
	s_mov_b32 m0, s66
	v_lshl_add_u64 v[210:211], s[30:31], 0, v[174:175]
	global_load_lds_dwordx4 v[210:211], off
	s_setprio 1
	s_waitcnt vmcnt(8) lgkmcnt(0)
	s_barrier
	v_mfma_f32_16x16x32_bf16 v[142:145], v[58:61], v[162:165], v[142:145]
	v_mfma_f32_16x16x32_bf16 v[138:141], v[66:69], v[162:165], v[138:141]
	v_mfma_f32_16x16x32_bf16 v[126:129], v[58:61], v[170:173], v[126:129]
	v_mfma_f32_16x16x32_bf16 v[122:125], v[66:69], v[170:173], v[122:125]
	v_mfma_f32_16x16x32_bf16 v[110:113], v[58:61], v[184:187], v[110:113]
	v_mfma_f32_16x16x32_bf16 v[106:109], v[66:69], v[184:187], v[106:109]
	v_mfma_f32_16x16x32_bf16 v[94:97], v[58:61], v[192:195], v[94:97]
	v_mfma_f32_16x16x32_bf16 v[90:93], v[66:69], v[192:195], v[90:93]
	v_mfma_f32_16x16x32_bf16 v[142:145], v[62:65], v[166:169], v[142:145]
	v_mfma_f32_16x16x32_bf16 v[138:141], v[70:73], v[166:169], v[138:141]
	v_mfma_f32_16x16x32_bf16 v[126:129], v[62:65], v[180:183], v[126:129]
	v_mfma_f32_16x16x32_bf16 v[122:125], v[70:73], v[180:183], v[122:125]
	v_mfma_f32_16x16x32_bf16 v[110:113], v[62:65], v[188:191], v[110:113]
	v_mfma_f32_16x16x32_bf16 v[106:109], v[70:73], v[188:191], v[106:109]
	v_mfma_f32_16x16x32_bf16 v[94:97], v[62:65], v[196:199], v[94:97]
	v_mfma_f32_16x16x32_bf16 v[90:93], v[70:73], v[196:199], v[90:93]
	v_mfma_f32_16x16x32_bf16 v[134:137], v[146:149], v[162:165], v[134:137]
	v_mfma_f32_16x16x32_bf16 v[130:133], v[154:157], v[162:165], v[130:133]
	v_mfma_f32_16x16x32_bf16 v[118:121], v[146:149], v[170:173], v[118:121]
	v_mfma_f32_16x16x32_bf16 v[114:117], v[154:157], v[170:173], v[114:117]
	v_mfma_f32_16x16x32_bf16 v[102:105], v[146:149], v[184:187], v[102:105]
	v_mfma_f32_16x16x32_bf16 v[98:101], v[154:157], v[184:187], v[98:101]
	v_mfma_f32_16x16x32_bf16 v[86:89], v[146:149], v[192:195], v[86:89]
	v_mfma_f32_16x16x32_bf16 v[82:85], v[154:157], v[192:195], v[82:85]
	v_mfma_f32_16x16x32_bf16 v[134:137], v[150:153], v[166:169], v[134:137]
	v_mfma_f32_16x16x32_bf16 v[130:133], v[158:161], v[166:169], v[130:133]
	v_mfma_f32_16x16x32_bf16 v[118:121], v[150:153], v[180:183], v[118:121]
	v_mfma_f32_16x16x32_bf16 v[114:117], v[158:161], v[180:183], v[114:117]
	v_mfma_f32_16x16x32_bf16 v[102:105], v[150:153], v[188:191], v[102:105]
	v_mfma_f32_16x16x32_bf16 v[98:101], v[158:161], v[188:191], v[98:101]
	v_mfma_f32_16x16x32_bf16 v[86:89], v[150:153], v[196:199], v[86:89]
	v_mfma_f32_16x16x32_bf16 v[82:85], v[158:161], v[196:199], v[82:85]
	s_setprio 0
	s_barrier
; #define PG8_STAGE(bufoff, gbase, voff) do { _Pragma("unroll") for (int _i = 0; _i < 2; ++_i) \
;         __builtin_amdgcn_global_load_lds((const unsigned*)((const char*)(gbase) + (voff)[_i]), (LAS unsigned*)(lds + (bufoff) + ldsw + _i * 8192), 16, 0, 0); } while (0)
; #define PG8_LDA(dst, b, h) do { _Pragma("unroll") for (int m = 0; m < 4; ++m) _Pragma("unroll") for (int k = 0; k < 2; ++k) dst[m][k] = *(const LAS bf16x8*)(lds + PG8_SA(b, h) + aoff + m * 2048 + k * 1024); } while (0)
; #define PG8_MMA(ai, bj, At, Bt) do { __builtin_amdgcn_s_setprio(1); _Pragma("unroll") for (int m = 0; m < 4; ++m) _Pragma("unroll") for (int n = 0; n < 2; ++n) _Pragma("unroll") for (int k = 0; k < 2; ++k) \
;         acc[ai][bj][m][n] = __builtin_amdgcn_mfma_f32_16x16x32_bf16(Bt[n][k], At[m][k], acc[ai][bj][m][n], 0, 0, 0); __builtin_amdgcn_s_setprio(0); } while (0)
; #define PG8_WAIT_V(n) asm volatile("s_waitcnt vmcnt(" #n ")" ::: "memory")
; #define PG8_WAIT_L(n) asm volatile("s_waitcnt lgkmcnt(" #n ")" ::: "memory")
; #define PG8_BAR __builtin_amdgcn_s_barrier()
; #define PG8_SCHED __builtin_amdgcn_sched_barrier(0)
; template <class Epi, int AMODE>
; __device__ __forceinline__ void gemm_phase(LAS unsigned char* lds, const Gemm g, const StaticOrder& S, const Epi& E, int stagger_us, int tid_in) {
;     ...
;             PG8_LDA(At, 1, 1); PG8_STAGE(PG8_SB(1, 0), b3, voffB); PG8_STAGE(PG8_SB(1, 1), b3 + hstepB, voffB); PG8_STAGE(PG8_SA(1, 0), a3, voffA);
;             PG8_WAIT_V(8); PG8_WAIT_L(0); PG8_BAR; PG8_MMA(1, 0, At, B0); PG8_MMA(1, 1, At, B1); PG8_BAR; PG8_SCHED;
;         }
;         if (wr == 0) PG8_BAR;
	ds_read_b128 v[162:165], v215 offset:49152
	ds_read_b128 v[166:169], v215 offset:50176
	ds_read_b128 v[170:173], v215 offset:51200
	ds_read_b128 v[180:183], v215 offset:52224
	ds_read_b128 v[184:187], v215 offset:53248
	ds_read_b128 v[188:191], v215 offset:54272
	ds_read_b128 v[192:195], v215 offset:55296
	ds_read_b128 v[196:199], v215 offset:56320
	s_add_i32 s30, s34, s12
	s_mov_b32 m0, s30
	v_lshl_add_u64 v[200:201], v[200:201], 0, s[74:75]
	global_load_lds_dwordx4 v[200:201], off
	s_add_i32 m0, s30, 0x2000
	s_add_u32 s6, s6, 0x158080
	v_lshl_add_u64 v[200:201], v[202:203], 0, s[74:75]
	s_addc_u32 s7, s7, 0
	s_add_i32 s30, s35, s12
	global_load_lds_dwordx4 v[200:201], off
	s_mov_b32 m0, s30
	v_lshl_add_u64 v[200:201], s[6:7], 0, v[0:1]
	global_load_lds_dwordx4 v[200:201], off
	s_add_i32 m0, s30, 0x2000
	v_lshl_add_u64 v[200:201], s[6:7], 0, v[174:175]
	global_load_lds_dwordx4 v[200:201], off
	s_mov_b32 m0, s79
	v_lshl_add_u64 v[200:201], v[204:205], 0, s[74:75]
	global_load_lds_dwordx4 v[200:201], off
	s_mov_b32 m0, s83
	v_lshl_add_u64 v[200:201], v[206:207], 0, s[74:75]
	global_load_lds_dwordx4 v[200:201], off
	s_setprio 1
	s_waitcnt vmcnt(8) lgkmcnt(0)
	s_barrier
	v_mfma_f32_16x16x32_bf16 v[78:81], v[58:61], v[162:165], v[78:81]
	v_mfma_f32_16x16x32_bf16 v[74:77], v[66:69], v[162:165], v[74:77]
	v_mfma_f32_16x16x32_bf16 v[46:49], v[58:61], v[170:173], v[46:49]
	v_mfma_f32_16x16x32_bf16 v[42:45], v[66:69], v[170:173], v[42:45]
	v_mfma_f32_16x16x32_bf16 v[30:33], v[58:61], v[184:187], v[30:33]
	v_mfma_f32_16x16x32_bf16 v[26:29], v[66:69], v[184:187], v[26:29]
	v_mfma_f32_16x16x32_bf16 v[14:17], v[58:61], v[192:195], v[14:17]
	v_mfma_f32_16x16x32_bf16 v[10:13], v[66:69], v[192:195], v[10:13]
	v_mfma_f32_16x16x32_bf16 v[78:81], v[62:65], v[166:169], v[78:81]
	v_mfma_f32_16x16x32_bf16 v[74:77], v[70:73], v[166:169], v[74:77]
	v_mfma_f32_16x16x32_bf16 v[46:49], v[62:65], v[180:183], v[46:49]
	v_mfma_f32_16x16x32_bf16 v[42:45], v[70:73], v[180:183], v[42:45]
	v_mfma_f32_16x16x32_bf16 v[30:33], v[62:65], v[188:191], v[30:33]
	v_mfma_f32_16x16x32_bf16 v[26:29], v[70:73], v[188:191], v[26:29]
	v_mfma_f32_16x16x32_bf16 v[14:17], v[62:65], v[196:199], v[14:17]
	v_mfma_f32_16x16x32_bf16 v[10:13], v[70:73], v[196:199], v[10:13]
	v_mfma_f32_16x16x32_bf16 v[50:53], v[146:149], v[162:165], v[50:53]
	v_mfma_f32_16x16x32_bf16 v[70:73], v[150:153], v[166:169], v[50:53]
	v_mfma_f32_16x16x32_bf16 v[50:53], v[154:157], v[162:165], v[54:57]
	v_mfma_f32_16x16x32_bf16 v[38:41], v[146:149], v[170:173], v[38:41]
	v_mfma_f32_16x16x32_bf16 v[34:37], v[154:157], v[170:173], v[34:37]
	v_mfma_f32_16x16x32_bf16 v[22:25], v[146:149], v[184:187], v[22:25]
	v_mfma_f32_16x16x32_bf16 v[18:21], v[154:157], v[184:187], v[18:21]
	v_mfma_f32_16x16x32_bf16 v[6:9], v[146:149], v[192:195], v[6:9]
	v_mfma_f32_16x16x32_bf16 v[2:5], v[154:157], v[192:195], v[2:5]
	v_mfma_f32_16x16x32_bf16 v[66:69], v[158:161], v[166:169], v[50:53]
	v_mfma_f32_16x16x32_bf16 v[38:41], v[150:153], v[180:183], v[38:41]
	v_mfma_f32_16x16x32_bf16 v[34:37], v[158:161], v[180:183], v[34:37]
	v_mfma_f32_16x16x32_bf16 v[22:25], v[150:153], v[188:191], v[22:25]
	v_mfma_f32_16x16x32_bf16 v[18:21], v[158:161], v[188:191], v[18:21]
	v_mfma_f32_16x16x32_bf16 v[6:9], v[150:153], v[196:199], v[6:9]
	v_mfma_f32_16x16x32_bf16 v[2:5], v[158:161], v[196:199], v[2:5]
	s_setprio 0
	s_barrier
	s_add_i32 s29, s29, 2
	s_add_u32 s27, s27, 0x100
	s_addc_u32 s28, s28, 0
	s_cmpk_gt_u32 s29, 0x53
	s_mov_b64 s[46:47], s[4:5]
	s_cbranch_scc0 .LBB0_1498
	s_and_b64 vcc, exec, s[54:55]
	s_cbranch_vccz .LBB0_1501
	s_barrier
